# v15 + Gray-code MFMA order in each 16-MFMA block (each MFMA shares accumulator or srcA or srcB with predecessor)
# speedup vs baseline: 1.0169x; 1.0114x over previous
.LBB0_364:
	s_add_u32 s20, s18, 0xfff80080
	s_addc_u32 s21, s19, -1
	s_add_i32 s30, 0, 0x10000
	s_cmp_eq_u32 s29, 28
	s_cselect_b32 s23, s4, s21
	s_cselect_b32 s22, s24, s20
	s_cselect_b32 s21, s25, s28
	s_cselect_b32 s20, s26, s27
	s_add_i32 s42, 0, 0x14000
	v_add_u32_e32 v142, s30, v204
	v_add_u32_e32 v166, s42, v204
	ds_read_b128 v[130:133], v142
	ds_read_b128 v[134:137], v142 offset:1024
	ds_read_b128 v[138:141], v142 offset:2048
	ds_read_b128 v[142:145], v142 offset:3072
	ds_read_b128 v[146:149], v166
	ds_read_b128 v[150:153], v166 offset:1024
	ds_read_b128 v[154:157], v166 offset:2048
	ds_read_b128 v[166:169], v166 offset:3072
	v_lshl_add_u64 v[202:203], s[18:19], 0, v[162:163]
	s_add_i32 m0, s87, 0xc000
	ds_read_b128 v[170:173], v205
	ds_read_b128 v[174:177], v205 offset:1024
	ds_read_b128 v[178:181], v205 offset:2048
	ds_read_b128 v[182:185], v205 offset:3072
	ds_read_b128 v[186:189], v205 offset:4096
	ds_read_b128 v[190:193], v205 offset:5120
	ds_read_b128 v[206:209], v205 offset:6144
	ds_read_b128 v[210:213], v205 offset:7168
	global_load_lds_dwordx4 v[202:203], off
	v_lshl_add_u64 v[202:203], s[18:19], 0, v[164:165]
	s_add_i32 m0, s87, 0xe000
	s_nop 0
	global_load_lds_dwordx4 v[202:203], off
	s_waitcnt vmcnt(8)
	s_waitcnt lgkmcnt(0)
	s_setprio 1
	s_barrier
	v_mfma_f32_16x16x32_bf16 v[126:129], v[130:133], v[170:173], v[126:129]
	v_mfma_f32_16x16x32_bf16 v[126:129], v[134:137], v[174:177], v[126:129]
	v_mfma_f32_16x16x32_bf16 v[122:125], v[142:145], v[174:177], v[122:125]
	v_mfma_f32_16x16x32_bf16 v[122:125], v[138:141], v[170:173], v[122:125]
	v_mfma_f32_16x16x32_bf16 v[106:109], v[138:141], v[178:181], v[106:109]
	v_mfma_f32_16x16x32_bf16 v[106:109], v[142:145], v[182:185], v[106:109]
	v_mfma_f32_16x16x32_bf16 v[110:113], v[134:137], v[182:185], v[110:113]
	v_mfma_f32_16x16x32_bf16 v[110:113], v[130:133], v[178:181], v[110:113]
	v_mfma_f32_16x16x32_bf16 v[94:97], v[130:133], v[186:189], v[94:97]
	v_mfma_f32_16x16x32_bf16 v[94:97], v[134:137], v[190:193], v[94:97]
	v_mfma_f32_16x16x32_bf16 v[90:93], v[142:145], v[190:193], v[90:93]
	v_mfma_f32_16x16x32_bf16 v[90:93], v[138:141], v[186:189], v[90:93]
	v_mfma_f32_16x16x32_bf16 v[74:77], v[138:141], v[206:209], v[74:77]
	v_mfma_f32_16x16x32_bf16 v[74:77], v[142:145], v[210:213], v[74:77]
	v_mfma_f32_16x16x32_bf16 v[78:81], v[134:137], v[210:213], v[78:81]
	v_mfma_f32_16x16x32_bf16 v[78:81], v[130:133], v[206:209], v[78:81]
	v_mfma_f32_16x16x32_bf16 v[118:121], v[146:149], v[170:173], v[118:121]
	v_mfma_f32_16x16x32_bf16 v[118:121], v[150:153], v[174:177], v[118:121]
	v_mfma_f32_16x16x32_bf16 v[114:117], v[166:169], v[174:177], v[114:117]
	v_mfma_f32_16x16x32_bf16 v[114:117], v[154:157], v[170:173], v[114:117]
	v_mfma_f32_16x16x32_bf16 v[98:101], v[154:157], v[178:181], v[98:101]
	v_mfma_f32_16x16x32_bf16 v[98:101], v[166:169], v[182:185], v[98:101]
	v_mfma_f32_16x16x32_bf16 v[102:105], v[150:153], v[182:185], v[102:105]
	v_mfma_f32_16x16x32_bf16 v[102:105], v[146:149], v[178:181], v[102:105]
	v_mfma_f32_16x16x32_bf16 v[86:89], v[146:149], v[186:189], v[86:89]
	v_mfma_f32_16x16x32_bf16 v[86:89], v[150:153], v[190:193], v[86:89]
	v_mfma_f32_16x16x32_bf16 v[82:85], v[166:169], v[190:193], v[82:85]
	v_mfma_f32_16x16x32_bf16 v[82:85], v[154:157], v[186:189], v[82:85]
	v_mfma_f32_16x16x32_bf16 v[66:69], v[154:157], v[206:209], v[66:69]
	v_mfma_f32_16x16x32_bf16 v[66:69], v[166:169], v[210:213], v[66:69]
	v_mfma_f32_16x16x32_bf16 v[70:73], v[150:153], v[210:213], v[70:73]
	v_mfma_f32_16x16x32_bf16 v[70:73], v[146:149], v[206:209], v[70:73]
	s_barrier
	s_setprio 0
	s_add_i32 s30, s30, s39
	v_lshl_add_u64 v[202:203], s[20:21], 0, v[158:159]
	s_mov_b32 m0, s30
	ds_read_b128 v[170:173], v205 offset:16384
	ds_read_b128 v[174:177], v205 offset:17408
	ds_read_b128 v[178:181], v205 offset:18432
	ds_read_b128 v[182:185], v205 offset:19456
	ds_read_b128 v[186:189], v205 offset:20480
	ds_read_b128 v[190:193], v205 offset:21504
	ds_read_b128 v[206:209], v205 offset:22528
	ds_read_b128 v[210:213], v205 offset:23552
	global_load_lds_dwordx4 v[202:203], off
	s_add_i32 m0, s30, 0x2000
	s_add_u32 s30, s20, 0x80000
	v_lshl_add_u64 v[214:215], s[20:21], 0, v[160:161]
	s_addc_u32 s31, s21, 0
	s_add_i32 s42, s42, s39
	global_load_lds_dwordx4 v[214:215], off
	v_lshl_add_u64 v[216:217], s[30:31], 0, v[158:159]
	s_mov_b32 m0, s42
	v_lshl_add_u64 v[228:229], s[22:23], 0, v[160:161]
	global_load_lds_dwordx4 v[216:217], off
	v_lshl_add_u64 v[216:217], s[30:31], 0, v[160:161]
	s_add_i32 m0, s42, 0x2000
	s_nop 0
	global_load_lds_dwordx4 v[216:217], off
	v_lshl_add_u64 v[216:217], s[22:23], 0, v[158:159]
	s_mov_b32 m0, s87
	s_nop 0
	global_load_lds_dwordx4 v[216:217], off
	s_mov_b32 m0, s92
	s_nop 0
	global_load_lds_dwordx4 v[228:229], off
	s_waitcnt vmcnt(8)
	s_waitcnt lgkmcnt(0)
	s_setprio 1
	s_barrier
	v_mfma_f32_16x16x32_bf16 v[62:65], v[130:133], v[170:173], v[62:65]
	v_mfma_f32_16x16x32_bf16 v[62:65], v[134:137], v[174:177], v[62:65]
	v_mfma_f32_16x16x32_bf16 v[58:61], v[142:145], v[174:177], v[58:61]
	v_mfma_f32_16x16x32_bf16 v[58:61], v[138:141], v[170:173], v[58:61]
	v_mfma_f32_16x16x32_bf16 v[42:45], v[138:141], v[178:181], v[42:45]
	v_mfma_f32_16x16x32_bf16 v[42:45], v[142:145], v[182:185], v[42:45]
	v_mfma_f32_16x16x32_bf16 v[46:49], v[134:137], v[182:185], v[46:49]
	v_mfma_f32_16x16x32_bf16 v[46:49], v[130:133], v[178:181], v[46:49]
	v_mfma_f32_16x16x32_bf16 v[30:33], v[130:133], v[186:189], v[30:33]
	v_mfma_f32_16x16x32_bf16 v[30:33], v[134:137], v[190:193], v[30:33]
	v_mfma_f32_16x16x32_bf16 v[26:29], v[142:145], v[190:193], v[26:29]
	v_mfma_f32_16x16x32_bf16 v[26:29], v[138:141], v[186:189], v[26:29]
	v_mfma_f32_16x16x32_bf16 v[10:13], v[138:141], v[206:209], v[10:13]
	v_mfma_f32_16x16x32_bf16 v[10:13], v[142:145], v[210:213], v[10:13]
	v_mfma_f32_16x16x32_bf16 v[14:17], v[134:137], v[210:213], v[14:17]
	v_mfma_f32_16x16x32_bf16 v[14:17], v[130:133], v[206:209], v[14:17]
	v_mfma_f32_16x16x32_bf16 v[54:57], v[146:149], v[170:173], v[54:57]
	v_mfma_f32_16x16x32_bf16 v[54:57], v[150:153], v[174:177], v[54:57]
	v_mfma_f32_16x16x32_bf16 v[50:53], v[166:169], v[174:177], v[50:53]
	v_mfma_f32_16x16x32_bf16 v[50:53], v[154:157], v[170:173], v[50:53]
	v_mfma_f32_16x16x32_bf16 v[34:37], v[154:157], v[178:181], v[34:37]
	v_mfma_f32_16x16x32_bf16 v[34:37], v[166:169], v[182:185], v[34:37]
	v_mfma_f32_16x16x32_bf16 v[38:41], v[150:153], v[182:185], v[38:41]
	v_mfma_f32_16x16x32_bf16 v[38:41], v[146:149], v[178:181], v[38:41]
	v_mfma_f32_16x16x32_bf16 v[22:25], v[146:149], v[186:189], v[22:25]
	v_mfma_f32_16x16x32_bf16 v[22:25], v[150:153], v[190:193], v[22:25]
	v_mfma_f32_16x16x32_bf16 v[18:21], v[166:169], v[190:193], v[18:21]
	v_mfma_f32_16x16x32_bf16 v[18:21], v[154:157], v[186:189], v[18:21]
	v_mfma_f32_16x16x32_bf16 v[2:5], v[154:157], v[206:209], v[2:5]
	v_mfma_f32_16x16x32_bf16 v[2:5], v[166:169], v[210:213], v[2:5]
	v_mfma_f32_16x16x32_bf16 v[6:9], v[150:153], v[210:213], v[6:9]
	v_mfma_f32_16x16x32_bf16 v[6:9], v[146:149], v[206:209], v[6:9]
	s_barrier
	s_setprio 0
	s_add_i32 s30, 0, 0x18000
	s_add_i32 s31, 0, 0x1c000
	v_add_u32_e32 v142, s30, v204
	v_add_u32_e32 v166, s31, v204
	ds_read_b128 v[130:133], v142
	ds_read_b128 v[134:137], v142 offset:1024
	ds_read_b128 v[138:141], v142 offset:2048
	ds_read_b128 v[142:145], v142 offset:3072
	ds_read_b128 v[146:149], v166
	ds_read_b128 v[150:153], v166 offset:1024
	ds_read_b128 v[154:157], v166 offset:2048
	ds_read_b128 v[166:169], v166 offset:3072
	s_add_u32 s22, s22, 0x80000
	s_addc_u32 s23, s23, 0
	s_mov_b32 m0, s8
	v_lshl_add_u64 v[230:231], s[22:23], 0, v[158:159]
	ds_read_b128 v[170:173], v205 offset:32768
	ds_read_b128 v[174:177], v205 offset:33792
	ds_read_b128 v[178:181], v205 offset:34816
	ds_read_b128 v[182:185], v205 offset:35840
	ds_read_b128 v[186:189], v205 offset:36864
	ds_read_b128 v[190:193], v205 offset:37888
	ds_read_b128 v[206:209], v205 offset:38912
	ds_read_b128 v[210:213], v205 offset:39936
	global_load_lds_dwordx4 v[230:231], off
	v_lshl_add_u64 v[230:231], s[22:23], 0, v[160:161]
	s_mov_b32 m0, s9
	s_nop 0
	global_load_lds_dwordx4 v[230:231], off
	s_waitcnt vmcnt(8)
	s_waitcnt lgkmcnt(0)
	s_setprio 1
	s_barrier
	v_mfma_f32_16x16x32_bf16 v[126:129], v[130:133], v[170:173], v[126:129]
	v_mfma_f32_16x16x32_bf16 v[126:129], v[134:137], v[174:177], v[126:129]
	v_mfma_f32_16x16x32_bf16 v[122:125], v[142:145], v[174:177], v[122:125]
	v_mfma_f32_16x16x32_bf16 v[122:125], v[138:141], v[170:173], v[122:125]
	v_mfma_f32_16x16x32_bf16 v[106:109], v[138:141], v[178:181], v[106:109]
	v_mfma_f32_16x16x32_bf16 v[106:109], v[142:145], v[182:185], v[106:109]
	v_mfma_f32_16x16x32_bf16 v[110:113], v[134:137], v[182:185], v[110:113]
	v_mfma_f32_16x16x32_bf16 v[110:113], v[130:133], v[178:181], v[110:113]
	v_mfma_f32_16x16x32_bf16 v[94:97], v[130:133], v[186:189], v[94:97]
	v_mfma_f32_16x16x32_bf16 v[94:97], v[134:137], v[190:193], v[94:97]
	v_mfma_f32_16x16x32_bf16 v[90:93], v[142:145], v[190:193], v[90:93]
	v_mfma_f32_16x16x32_bf16 v[90:93], v[138:141], v[186:189], v[90:93]
	v_mfma_f32_16x16x32_bf16 v[74:77], v[138:141], v[206:209], v[74:77]
	v_mfma_f32_16x16x32_bf16 v[74:77], v[142:145], v[210:213], v[74:77]
	v_mfma_f32_16x16x32_bf16 v[78:81], v[134:137], v[210:213], v[78:81]
	v_mfma_f32_16x16x32_bf16 v[78:81], v[130:133], v[206:209], v[78:81]
	v_mfma_f32_16x16x32_bf16 v[118:121], v[146:149], v[170:173], v[118:121]
	v_mfma_f32_16x16x32_bf16 v[118:121], v[150:153], v[174:177], v[118:121]
	v_mfma_f32_16x16x32_bf16 v[114:117], v[166:169], v[174:177], v[114:117]
	v_mfma_f32_16x16x32_bf16 v[114:117], v[154:157], v[170:173], v[114:117]
	v_mfma_f32_16x16x32_bf16 v[98:101], v[154:157], v[178:181], v[98:101]
	v_mfma_f32_16x16x32_bf16 v[98:101], v[166:169], v[182:185], v[98:101]
	v_mfma_f32_16x16x32_bf16 v[102:105], v[150:153], v[182:185], v[102:105]
	v_mfma_f32_16x16x32_bf16 v[102:105], v[146:149], v[178:181], v[102:105]
	v_mfma_f32_16x16x32_bf16 v[86:89], v[146:149], v[186:189], v[86:89]
	v_mfma_f32_16x16x32_bf16 v[86:89], v[150:153], v[190:193], v[86:89]
	v_mfma_f32_16x16x32_bf16 v[82:85], v[166:169], v[190:193], v[82:85]
	v_mfma_f32_16x16x32_bf16 v[82:85], v[154:157], v[186:189], v[82:85]
	v_mfma_f32_16x16x32_bf16 v[66:69], v[154:157], v[206:209], v[66:69]
	v_mfma_f32_16x16x32_bf16 v[66:69], v[166:169], v[210:213], v[66:69]
	v_mfma_f32_16x16x32_bf16 v[70:73], v[150:153], v[210:213], v[70:73]
	v_mfma_f32_16x16x32_bf16 v[70:73], v[146:149], v[206:209], v[70:73]
	s_barrier
	s_setprio 0
	s_add_i32 s22, s30, s39
	v_lshl_add_u64 v[202:203], v[202:203], 0, s[10:11]
	s_mov_b32 m0, s22
	ds_read_b128 v[170:173], v205 offset:49152
	ds_read_b128 v[174:177], v205 offset:50176
	ds_read_b128 v[178:181], v205 offset:51200
	ds_read_b128 v[182:185], v205 offset:52224
	ds_read_b128 v[186:189], v205 offset:53248
	ds_read_b128 v[190:193], v205 offset:54272
	ds_read_b128 v[206:209], v205 offset:55296
	ds_read_b128 v[210:213], v205 offset:56320
	global_load_lds_dwordx4 v[202:203], off
	s_add_i32 m0, s22, 0x2000
	s_add_u32 s20, s20, 0x80080
	v_lshl_add_u64 v[202:203], v[214:215], 0, s[10:11]
	s_addc_u32 s21, s21, 0
	s_add_i32 s22, s31, s39
	global_load_lds_dwordx4 v[202:203], off
	v_lshl_add_u64 v[202:203], s[20:21], 0, v[158:159]
	s_mov_b32 m0, s22
	s_nop 0
	global_load_lds_dwordx4 v[202:203], off
	v_lshl_add_u64 v[202:203], s[20:21], 0, v[160:161]
	s_add_i32 m0, s22, 0x2000
	s_nop 0
	global_load_lds_dwordx4 v[202:203], off
	v_lshl_add_u64 v[202:203], v[216:217], 0, s[10:11]
	s_mov_b32 m0, s56
	s_nop 0
	global_load_lds_dwordx4 v[202:203], off
	v_lshl_add_u64 v[202:203], v[228:229], 0, s[10:11]
	s_mov_b32 m0, s57
	s_nop 0
	global_load_lds_dwordx4 v[202:203], off
	s_waitcnt vmcnt(8)
	s_waitcnt lgkmcnt(0)
	s_setprio 1
	s_barrier
	v_mfma_f32_16x16x32_bf16 v[62:65], v[130:133], v[170:173], v[62:65]
	v_mfma_f32_16x16x32_bf16 v[62:65], v[134:137], v[174:177], v[62:65]
	v_mfma_f32_16x16x32_bf16 v[58:61], v[142:145], v[174:177], v[58:61]
	v_mfma_f32_16x16x32_bf16 v[58:61], v[138:141], v[170:173], v[58:61]
	v_mfma_f32_16x16x32_bf16 v[42:45], v[138:141], v[178:181], v[42:45]
	v_mfma_f32_16x16x32_bf16 v[42:45], v[142:145], v[182:185], v[42:45]
	v_mfma_f32_16x16x32_bf16 v[46:49], v[134:137], v[182:185], v[46:49]
	v_mfma_f32_16x16x32_bf16 v[46:49], v[130:133], v[178:181], v[46:49]
	v_mfma_f32_16x16x32_bf16 v[30:33], v[130:133], v[186:189], v[30:33]
	v_mfma_f32_16x16x32_bf16 v[30:33], v[134:137], v[190:193], v[30:33]
	v_mfma_f32_16x16x32_bf16 v[26:29], v[142:145], v[190:193], v[26:29]
	v_mfma_f32_16x16x32_bf16 v[26:29], v[138:141], v[186:189], v[26:29]
	v_mfma_f32_16x16x32_bf16 v[10:13], v[138:141], v[206:209], v[10:13]
	v_mfma_f32_16x16x32_bf16 v[10:13], v[142:145], v[210:213], v[10:13]
	v_mfma_f32_16x16x32_bf16 v[14:17], v[134:137], v[210:213], v[14:17]
	v_mfma_f32_16x16x32_bf16 v[14:17], v[130:133], v[206:209], v[14:17]
	v_mfma_f32_16x16x32_bf16 v[54:57], v[146:149], v[170:173], v[54:57]
	v_mfma_f32_16x16x32_bf16 v[54:57], v[150:153], v[174:177], v[54:57]
	v_mfma_f32_16x16x32_bf16 v[50:53], v[166:169], v[174:177], v[50:53]
	v_mfma_f32_16x16x32_bf16 v[50:53], v[154:157], v[170:173], v[50:53]
	v_mfma_f32_16x16x32_bf16 v[34:37], v[154:157], v[178:181], v[34:37]
	v_mfma_f32_16x16x32_bf16 v[34:37], v[166:169], v[182:185], v[34:37]
	v_mfma_f32_16x16x32_bf16 v[38:41], v[150:153], v[182:185], v[38:41]
	v_mfma_f32_16x16x32_bf16 v[38:41], v[146:149], v[178:181], v[38:41]
	v_mfma_f32_16x16x32_bf16 v[22:25], v[146:149], v[186:189], v[22:25]
	v_mfma_f32_16x16x32_bf16 v[22:25], v[150:153], v[190:193], v[22:25]
	v_mfma_f32_16x16x32_bf16 v[18:21], v[166:169], v[190:193], v[18:21]
	v_mfma_f32_16x16x32_bf16 v[18:21], v[154:157], v[186:189], v[18:21]
	v_mfma_f32_16x16x32_bf16 v[2:5], v[154:157], v[206:209], v[2:5]
	v_mfma_f32_16x16x32_bf16 v[2:5], v[166:169], v[210:213], v[2:5]
	v_mfma_f32_16x16x32_bf16 v[6:9], v[150:153], v[210:213], v[6:9]
	v_mfma_f32_16x16x32_bf16 v[6:9], v[146:149], v[206:209], v[6:9]
	s_barrier
	s_setprio 0
	s_add_i32 s29, s29, 2
	s_add_u32 s18, s18, 0x100
	s_addc_u32 s19, s19, 0
	s_add_u32 s27, s27, 0x100
	s_addc_u32 s28, s28, 0
	s_cmp_gt_u32 s29, 29
	s_cbranch_scc0 .LBB0_364
	s_and_b64 vcc, exec, s[58:59]
	s_cbranch_vccz .LBB0_367
	s_barrier

.LBB0_986:
	s_add_u32 s24, s22, 0x100
	s_addc_u32 s25, s23, 0
	s_add_i32 s62, 0, 0x10000
	s_cmp_eq_u32 s61, 28
	s_cselect_b32 s29, s17, s25
	s_cselect_b32 s28, s58, s24
	v_add_u32_e32 v138, s62, v140
	s_cselect_b32 s27, s19, s60
	s_cselect_b32 s26, s18, s59
	s_add_i32 s63, 0, 0x14000
	ds_read_b128 v[142:145], v138
	ds_read_b128 v[146:149], v138 offset:1024
	ds_read_b128 v[150:153], v138 offset:2048
	ds_read_b128 v[154:157], v138 offset:3072
	v_add_u32_e32 v138, s63, v140
	ds_read_b128 v[158:161], v138
	ds_read_b128 v[162:165], v138 offset:1024
	ds_read_b128 v[166:169], v138 offset:2048
	ds_read_b128 v[170:173], v138 offset:3072
	v_lshl_add_u64 v[138:139], s[22:23], 0, v[134:135]
	s_add_i32 m0, s47, 0xc000
	ds_read_b128 v[174:177], v141
	ds_read_b128 v[178:181], v141 offset:1024
	ds_read_b128 v[182:185], v141 offset:2048
	ds_read_b128 v[186:189], v141 offset:3072
	ds_read_b128 v[190:193], v141 offset:4096
	ds_read_b128 v[202:205], v141 offset:5120
	ds_read_b128 v[206:209], v141 offset:6144
	ds_read_b128 v[210:213], v141 offset:7168
	global_load_lds_dwordx4 v[138:139], off
	v_lshl_add_u64 v[138:139], s[22:23], 0, v[136:137]
	s_add_i32 m0, s47, 0xe000
	s_nop 0
	global_load_lds_dwordx4 v[138:139], off
	s_waitcnt vmcnt(8)
	s_waitcnt lgkmcnt(0)
	s_setprio 1
	s_barrier
	v_mfma_f32_16x16x32_bf16 v[126:129], v[142:145], v[174:177], v[126:129]
	v_mfma_f32_16x16x32_bf16 v[126:129], v[146:149], v[178:181], v[126:129]
	v_mfma_f32_16x16x32_bf16 v[122:125], v[154:157], v[178:181], v[122:125]
	v_mfma_f32_16x16x32_bf16 v[122:125], v[150:153], v[174:177], v[122:125]
	v_mfma_f32_16x16x32_bf16 v[110:113], v[150:153], v[182:185], v[110:113]
	v_mfma_f32_16x16x32_bf16 v[110:113], v[154:157], v[186:189], v[110:113]
	v_mfma_f32_16x16x32_bf16 v[118:121], v[146:149], v[186:189], v[118:121]
	v_mfma_f32_16x16x32_bf16 v[118:121], v[142:145], v[182:185], v[118:121]
	v_mfma_f32_16x16x32_bf16 v[102:105], v[142:145], v[190:193], v[102:105]
	v_mfma_f32_16x16x32_bf16 v[102:105], v[146:149], v[202:205], v[102:105]
	v_mfma_f32_16x16x32_bf16 v[94:97], v[154:157], v[202:205], v[94:97]
	v_mfma_f32_16x16x32_bf16 v[94:97], v[150:153], v[190:193], v[94:97]
	v_mfma_f32_16x16x32_bf16 v[78:81], v[150:153], v[206:209], v[78:81]
	v_mfma_f32_16x16x32_bf16 v[78:81], v[154:157], v[210:213], v[78:81]
	v_mfma_f32_16x16x32_bf16 v[86:89], v[146:149], v[210:213], v[86:89]
	v_mfma_f32_16x16x32_bf16 v[86:89], v[142:145], v[206:209], v[86:89]
	v_mfma_f32_16x16x32_bf16 v[114:117], v[158:161], v[174:177], v[114:117]
	v_mfma_f32_16x16x32_bf16 v[114:117], v[162:165], v[178:181], v[114:117]
	v_mfma_f32_16x16x32_bf16 v[106:109], v[170:173], v[178:181], v[106:109]
	v_mfma_f32_16x16x32_bf16 v[106:109], v[166:169], v[174:177], v[106:109]
	v_mfma_f32_16x16x32_bf16 v[90:93], v[166:169], v[182:185], v[90:93]
	v_mfma_f32_16x16x32_bf16 v[90:93], v[170:173], v[186:189], v[90:93]
	v_mfma_f32_16x16x32_bf16 v[98:101], v[162:165], v[186:189], v[98:101]
	v_mfma_f32_16x16x32_bf16 v[98:101], v[158:161], v[182:185], v[98:101]
	v_mfma_f32_16x16x32_bf16 v[82:85], v[158:161], v[190:193], v[82:85]
	v_mfma_f32_16x16x32_bf16 v[82:85], v[162:165], v[202:205], v[82:85]
	v_mfma_f32_16x16x32_bf16 v[74:77], v[170:173], v[202:205], v[74:77]
	v_mfma_f32_16x16x32_bf16 v[74:77], v[166:169], v[190:193], v[74:77]
	v_mfma_f32_16x16x32_bf16 v[66:69], v[166:169], v[206:209], v[66:69]
	v_mfma_f32_16x16x32_bf16 v[66:69], v[170:173], v[210:213], v[66:69]
	v_mfma_f32_16x16x32_bf16 v[70:73], v[162:165], v[210:213], v[70:73]
	v_mfma_f32_16x16x32_bf16 v[70:73], v[158:161], v[206:209], v[70:73]
	s_barrier
	s_setprio 0
	s_add_i32 s22, s62, s36
	v_lshl_add_u64 v[138:139], s[26:27], 0, v[132:133]
	s_mov_b32 m0, s22
	ds_read_b128 v[174:177], v141 offset:16384
	ds_read_b128 v[178:181], v141 offset:17408
	ds_read_b128 v[182:185], v141 offset:18432
	ds_read_b128 v[186:189], v141 offset:19456
	ds_read_b128 v[190:193], v141 offset:20480
	ds_read_b128 v[202:205], v141 offset:21504
	ds_read_b128 v[206:209], v141 offset:22528
	ds_read_b128 v[210:213], v141 offset:23552
	global_load_lds_dwordx4 v[138:139], off
	s_add_i32 m0, s22, 0x2000
	s_add_u32 s22, s26, 0x80000
	v_lshl_add_u64 v[214:215], s[26:27], 0, v[130:131]
	s_addc_u32 s23, s27, 0
	s_add_i32 s62, s63, s36
	global_load_lds_dwordx4 v[214:215], off
	v_lshl_add_u64 v[216:217], s[22:23], 0, v[132:133]
	s_mov_b32 m0, s62
	v_lshl_add_u64 v[228:229], s[28:29], 0, v[130:131]
	global_load_lds_dwordx4 v[216:217], off
	v_lshl_add_u64 v[216:217], s[22:23], 0, v[130:131]
	s_add_i32 m0, s62, 0x2000
	s_nop 0
	global_load_lds_dwordx4 v[216:217], off
	v_lshl_add_u64 v[216:217], s[28:29], 0, v[132:133]
	s_mov_b32 m0, s47
	s_nop 0
	global_load_lds_dwordx4 v[216:217], off
	s_mov_b32 m0, s48
	s_nop 0
	global_load_lds_dwordx4 v[228:229], off
	s_waitcnt vmcnt(8)
	s_waitcnt lgkmcnt(0)
	s_setprio 1
	s_barrier
	v_mfma_f32_16x16x32_bf16 v[62:65], v[142:145], v[174:177], v[62:65]
	v_mfma_f32_16x16x32_bf16 v[62:65], v[146:149], v[178:181], v[62:65]
	v_mfma_f32_16x16x32_bf16 v[58:61], v[154:157], v[178:181], v[58:61]
	v_mfma_f32_16x16x32_bf16 v[58:61], v[150:153], v[174:177], v[58:61]
	v_mfma_f32_16x16x32_bf16 v[46:49], v[150:153], v[182:185], v[46:49]
	v_mfma_f32_16x16x32_bf16 v[46:49], v[154:157], v[186:189], v[46:49]
	v_mfma_f32_16x16x32_bf16 v[54:57], v[146:149], v[186:189], v[54:57]
	v_mfma_f32_16x16x32_bf16 v[54:57], v[142:145], v[182:185], v[54:57]
	v_mfma_f32_16x16x32_bf16 v[38:41], v[142:145], v[190:193], v[38:41]
	v_mfma_f32_16x16x32_bf16 v[38:41], v[146:149], v[202:205], v[38:41]
	v_mfma_f32_16x16x32_bf16 v[30:33], v[154:157], v[202:205], v[30:33]
	v_mfma_f32_16x16x32_bf16 v[30:33], v[150:153], v[190:193], v[30:33]
	v_mfma_f32_16x16x32_bf16 v[14:17], v[150:153], v[206:209], v[14:17]
	v_mfma_f32_16x16x32_bf16 v[14:17], v[154:157], v[210:213], v[14:17]
	v_mfma_f32_16x16x32_bf16 v[22:25], v[146:149], v[210:213], v[22:25]
	v_mfma_f32_16x16x32_bf16 v[22:25], v[142:145], v[206:209], v[22:25]
	v_mfma_f32_16x16x32_bf16 v[50:53], v[158:161], v[174:177], v[50:53]
	v_mfma_f32_16x16x32_bf16 v[50:53], v[162:165], v[178:181], v[50:53]
	v_mfma_f32_16x16x32_bf16 v[42:45], v[170:173], v[178:181], v[42:45]
	v_mfma_f32_16x16x32_bf16 v[42:45], v[166:169], v[174:177], v[42:45]
	v_mfma_f32_16x16x32_bf16 v[26:29], v[166:169], v[182:185], v[26:29]
	v_mfma_f32_16x16x32_bf16 v[26:29], v[170:173], v[186:189], v[26:29]
	v_mfma_f32_16x16x32_bf16 v[34:37], v[162:165], v[186:189], v[34:37]
	v_mfma_f32_16x16x32_bf16 v[34:37], v[158:161], v[182:185], v[34:37]
	v_mfma_f32_16x16x32_bf16 v[18:21], v[158:161], v[190:193], v[18:21]
	v_mfma_f32_16x16x32_bf16 v[18:21], v[162:165], v[202:205], v[18:21]
	v_mfma_f32_16x16x32_bf16 v[10:13], v[170:173], v[202:205], v[10:13]
	v_mfma_f32_16x16x32_bf16 v[10:13], v[166:169], v[190:193], v[10:13]
	v_mfma_f32_16x16x32_bf16 v[2:5], v[166:169], v[206:209], v[2:5]
	v_mfma_f32_16x16x32_bf16 v[2:5], v[170:173], v[210:213], v[2:5]
	v_mfma_f32_16x16x32_bf16 v[6:9], v[162:165], v[210:213], v[6:9]
	v_mfma_f32_16x16x32_bf16 v[6:9], v[158:161], v[206:209], v[6:9]
	s_barrier
	s_setprio 0
	s_add_i32 s62, 0, 0x18000
	s_add_i32 s63, 0, 0x1c000
	v_add_u32_e32 v154, s62, v140
	v_add_u32_e32 v170, s63, v140
	ds_read_b128 v[142:145], v154
	ds_read_b128 v[146:149], v154 offset:1024
	ds_read_b128 v[150:153], v154 offset:2048
	ds_read_b128 v[154:157], v154 offset:3072
	ds_read_b128 v[158:161], v170
	ds_read_b128 v[162:165], v170 offset:1024
	ds_read_b128 v[166:169], v170 offset:2048
	ds_read_b128 v[170:173], v170 offset:3072
	s_add_u32 s22, s28, 0x80000
	s_addc_u32 s23, s29, 0
	s_mov_b32 m0, s49
	v_lshl_add_u64 v[230:231], s[22:23], 0, v[132:133]
	ds_read_b128 v[174:177], v141 offset:32768
	ds_read_b128 v[178:181], v141 offset:33792
	ds_read_b128 v[182:185], v141 offset:34816
	ds_read_b128 v[186:189], v141 offset:35840
	ds_read_b128 v[190:193], v141 offset:36864
	ds_read_b128 v[202:205], v141 offset:37888
	ds_read_b128 v[206:209], v141 offset:38912
	ds_read_b128 v[210:213], v141 offset:39936
	global_load_lds_dwordx4 v[230:231], off
	v_lshl_add_u64 v[230:231], s[22:23], 0, v[130:131]
	s_mov_b32 m0, s50
	s_nop 0
	global_load_lds_dwordx4 v[230:231], off
	s_waitcnt vmcnt(8)
	s_waitcnt lgkmcnt(0)
	s_setprio 1
	s_barrier
	v_mfma_f32_16x16x32_bf16 v[126:129], v[142:145], v[174:177], v[126:129]
	v_mfma_f32_16x16x32_bf16 v[126:129], v[146:149], v[178:181], v[126:129]
	v_mfma_f32_16x16x32_bf16 v[122:125], v[154:157], v[178:181], v[122:125]
	v_mfma_f32_16x16x32_bf16 v[122:125], v[150:153], v[174:177], v[122:125]
	v_mfma_f32_16x16x32_bf16 v[110:113], v[150:153], v[182:185], v[110:113]
	v_mfma_f32_16x16x32_bf16 v[110:113], v[154:157], v[186:189], v[110:113]
	v_mfma_f32_16x16x32_bf16 v[118:121], v[146:149], v[186:189], v[118:121]
	v_mfma_f32_16x16x32_bf16 v[118:121], v[142:145], v[182:185], v[118:121]
	v_mfma_f32_16x16x32_bf16 v[102:105], v[142:145], v[190:193], v[102:105]
	v_mfma_f32_16x16x32_bf16 v[102:105], v[146:149], v[202:205], v[102:105]
	v_mfma_f32_16x16x32_bf16 v[94:97], v[154:157], v[202:205], v[94:97]
	v_mfma_f32_16x16x32_bf16 v[94:97], v[150:153], v[190:193], v[94:97]
	v_mfma_f32_16x16x32_bf16 v[78:81], v[150:153], v[206:209], v[78:81]
	v_mfma_f32_16x16x32_bf16 v[78:81], v[154:157], v[210:213], v[78:81]
	v_mfma_f32_16x16x32_bf16 v[86:89], v[146:149], v[210:213], v[86:89]
	v_mfma_f32_16x16x32_bf16 v[86:89], v[142:145], v[206:209], v[86:89]
	v_mfma_f32_16x16x32_bf16 v[114:117], v[158:161], v[174:177], v[114:117]
	v_mfma_f32_16x16x32_bf16 v[114:117], v[162:165], v[178:181], v[114:117]
	v_mfma_f32_16x16x32_bf16 v[106:109], v[170:173], v[178:181], v[106:109]
	v_mfma_f32_16x16x32_bf16 v[106:109], v[166:169], v[174:177], v[106:109]
	v_mfma_f32_16x16x32_bf16 v[90:93], v[166:169], v[182:185], v[90:93]
	v_mfma_f32_16x16x32_bf16 v[90:93], v[170:173], v[186:189], v[90:93]
	v_mfma_f32_16x16x32_bf16 v[98:101], v[162:165], v[186:189], v[98:101]
	v_mfma_f32_16x16x32_bf16 v[98:101], v[158:161], v[182:185], v[98:101]
	v_mfma_f32_16x16x32_bf16 v[82:85], v[158:161], v[190:193], v[82:85]
	v_mfma_f32_16x16x32_bf16 v[82:85], v[162:165], v[202:205], v[82:85]
	v_mfma_f32_16x16x32_bf16 v[74:77], v[170:173], v[202:205], v[74:77]
	v_mfma_f32_16x16x32_bf16 v[74:77], v[166:169], v[190:193], v[74:77]
	v_mfma_f32_16x16x32_bf16 v[66:69], v[166:169], v[206:209], v[66:69]
	v_mfma_f32_16x16x32_bf16 v[66:69], v[170:173], v[210:213], v[66:69]
	v_mfma_f32_16x16x32_bf16 v[70:73], v[162:165], v[210:213], v[70:73]
	v_mfma_f32_16x16x32_bf16 v[70:73], v[158:161], v[206:209], v[70:73]
	s_barrier
	s_setprio 0
	s_add_i32 s22, s62, s36
	v_lshl_add_u64 v[138:139], v[138:139], 0, s[10:11]
	s_mov_b32 m0, s22
	ds_read_b128 v[174:177], v141 offset:49152
	ds_read_b128 v[178:181], v141 offset:50176
	ds_read_b128 v[182:185], v141 offset:51200
	ds_read_b128 v[186:189], v141 offset:52224
	ds_read_b128 v[190:193], v141 offset:53248
	ds_read_b128 v[202:205], v141 offset:54272
	ds_read_b128 v[206:209], v141 offset:55296
	ds_read_b128 v[210:213], v141 offset:56320
	global_load_lds_dwordx4 v[138:139], off
	s_add_i32 m0, s22, 0x2000
	s_add_u32 s22, s26, 0x80080
	v_lshl_add_u64 v[138:139], v[214:215], 0, s[10:11]
	s_addc_u32 s23, s27, 0
	s_add_i32 s26, s63, s36
	global_load_lds_dwordx4 v[138:139], off
	v_lshl_add_u64 v[138:139], s[22:23], 0, v[132:133]
	s_mov_b32 m0, s26
	s_nop 0
	global_load_lds_dwordx4 v[138:139], off
	v_lshl_add_u64 v[138:139], s[22:23], 0, v[130:131]
	s_add_i32 m0, s26, 0x2000
	s_nop 0
	global_load_lds_dwordx4 v[138:139], off
	v_lshl_add_u64 v[138:139], v[216:217], 0, s[10:11]
	s_mov_b32 m0, s51
	s_nop 0
	global_load_lds_dwordx4 v[138:139], off
	v_lshl_add_u64 v[138:139], v[228:229], 0, s[10:11]
	s_mov_b32 m0, s52
	s_nop 0
	global_load_lds_dwordx4 v[138:139], off
	s_waitcnt vmcnt(8)
	s_waitcnt lgkmcnt(0)
	s_setprio 1
	s_barrier
	v_mfma_f32_16x16x32_bf16 v[62:65], v[142:145], v[174:177], v[62:65]
	v_mfma_f32_16x16x32_bf16 v[62:65], v[146:149], v[178:181], v[62:65]
	v_mfma_f32_16x16x32_bf16 v[58:61], v[154:157], v[178:181], v[58:61]
	v_mfma_f32_16x16x32_bf16 v[58:61], v[150:153], v[174:177], v[58:61]
	v_mfma_f32_16x16x32_bf16 v[46:49], v[150:153], v[182:185], v[46:49]
	v_mfma_f32_16x16x32_bf16 v[46:49], v[154:157], v[186:189], v[46:49]
	v_mfma_f32_16x16x32_bf16 v[54:57], v[146:149], v[186:189], v[54:57]
	v_mfma_f32_16x16x32_bf16 v[54:57], v[142:145], v[182:185], v[54:57]
	v_mfma_f32_16x16x32_bf16 v[38:41], v[142:145], v[190:193], v[38:41]
	v_mfma_f32_16x16x32_bf16 v[38:41], v[146:149], v[202:205], v[38:41]
	v_mfma_f32_16x16x32_bf16 v[30:33], v[154:157], v[202:205], v[30:33]
	v_mfma_f32_16x16x32_bf16 v[30:33], v[150:153], v[190:193], v[30:33]
	v_mfma_f32_16x16x32_bf16 v[14:17], v[150:153], v[206:209], v[14:17]
	v_mfma_f32_16x16x32_bf16 v[14:17], v[154:157], v[210:213], v[14:17]
	v_mfma_f32_16x16x32_bf16 v[22:25], v[146:149], v[210:213], v[22:25]
	v_mfma_f32_16x16x32_bf16 v[22:25], v[142:145], v[206:209], v[22:25]
	v_mfma_f32_16x16x32_bf16 v[50:53], v[158:161], v[174:177], v[50:53]
	v_mfma_f32_16x16x32_bf16 v[50:53], v[162:165], v[178:181], v[50:53]
	v_mfma_f32_16x16x32_bf16 v[42:45], v[170:173], v[178:181], v[42:45]
	v_mfma_f32_16x16x32_bf16 v[42:45], v[166:169], v[174:177], v[42:45]
	v_mfma_f32_16x16x32_bf16 v[26:29], v[166:169], v[182:185], v[26:29]
	v_mfma_f32_16x16x32_bf16 v[26:29], v[170:173], v[186:189], v[26:29]
	v_mfma_f32_16x16x32_bf16 v[34:37], v[162:165], v[186:189], v[34:37]
	v_mfma_f32_16x16x32_bf16 v[34:37], v[158:161], v[182:185], v[34:37]
	v_mfma_f32_16x16x32_bf16 v[18:21], v[158:161], v[190:193], v[18:21]
	v_mfma_f32_16x16x32_bf16 v[18:21], v[162:165], v[202:205], v[18:21]
	v_mfma_f32_16x16x32_bf16 v[10:13], v[170:173], v[202:205], v[10:13]
	v_mfma_f32_16x16x32_bf16 v[10:13], v[166:169], v[190:193], v[10:13]
	v_mfma_f32_16x16x32_bf16 v[2:5], v[166:169], v[206:209], v[2:5]
	v_mfma_f32_16x16x32_bf16 v[2:5], v[170:173], v[210:213], v[2:5]
	v_mfma_f32_16x16x32_bf16 v[6:9], v[162:165], v[210:213], v[6:9]
	v_mfma_f32_16x16x32_bf16 v[6:9], v[158:161], v[206:209], v[6:9]
	s_barrier
	s_setprio 0
	s_add_i32 s61, s61, 2
	s_add_u32 s59, s59, 0x100
	s_addc_u32 s60, s60, 0
	s_cmp_gt_u32 s61, 29
	s_mov_b64 s[22:23], s[24:25]
	s_cbranch_scc0 .LBB0_986
	s_and_b64 vcc, exec, s[14:15]
	s_cbranch_vccz .LBB0_989
	s_barrier

.LBB0_1002:
	s_add_i32 s36, s21, 0x100
	s_and_b64 s[30:31], s[28:29], exec
	s_cselect_b32 s31, 0, s36
	s_cselect_b32 s30, 0, 0
	s_add_u32 s36, s8, s31
	s_addc_u32 s37, s9, s30
	s_add_u32 s30, s24, s21
	s_addc_u32 s31, s25, 0
	s_add_u32 s30, s30, 0x100
	s_addc_u32 s31, s31, 0
	s_add_i32 s71, 0, 0x10000
	s_and_b64 s[28:29], s[28:29], exec
	s_cselect_b32 s39, s19, s31
	s_cselect_b32 s38, s18, s30
	s_add_i32 s29, 0, 0x14000
	s_add_u32 s21, s44, s21
	s_addc_u32 s28, s45, 0
	s_add_u32 s48, s21, 0x17110080
	s_addc_u32 s49, s28, 0
	s_add_i32 s70, s71, s52
	s_add_i32 m0, s53, 0xc000
	s_add_i32 s73, s53, 0xe000
	s_add_i32 s67, s70, 0x2000
	v_add_u32_e32 v134, s71, v136
	s_add_u32 s46, s38, 0x10000
	ds_read_b128 v[138:141], v134
	ds_read_b128 v[142:145], v134 offset:1024
	ds_read_b128 v[146:149], v134 offset:2048
	ds_read_b128 v[150:153], v134 offset:3072
	v_add_u32_e32 v134, s29, v136
	s_addc_u32 s47, s39, 0
	s_add_i32 s69, s29, s52
	ds_read_b128 v[154:157], v134
	ds_read_b128 v[158:161], v134 offset:1024
	ds_read_b128 v[162:165], v134 offset:2048
	ds_read_b128 v[166:169], v134 offset:3072
	s_add_i32 s68, s69, 0x2000
	s_add_i32 s66, 0, 0x18000
	s_add_i32 s65, 0, 0x1c000
	s_add_u32 s30, s36, 0x10000
	s_addc_u32 s31, s37, 0
	s_add_i32 s64, s66, s52
	s_add_i32 s21, s64, 0x2000
	s_add_u32 s28, s38, 0x10080
	s_addc_u32 s29, s39, 0
	s_add_i32 s72, s65, s52
	s_add_i32 s71, s72, 0x2000
	v_lshl_add_u64 v[134:135], s[48:49], 0, v[132:133]
	ds_read_b128 v[170:173], v137
	ds_read_b128 v[174:177], v137 offset:1024
	ds_read_b128 v[178:181], v137 offset:2048
	ds_read_b128 v[182:185], v137 offset:3072
	ds_read_b128 v[186:189], v137 offset:4096
	ds_read_b128 v[190:193], v137 offset:5120
	ds_read_b128 v[202:205], v137 offset:6144
	ds_read_b128 v[206:209], v137 offset:7168
	global_load_lds_dwordx4 v[134:135], off
	v_lshl_add_u64 v[134:135], s[48:49], 0, v[130:131]
	s_mov_b32 m0, s73
	s_nop 0
	global_load_lds_dwordx4 v[134:135], off
	s_waitcnt vmcnt(8)
	s_waitcnt lgkmcnt(0)
	s_setprio 1
	s_barrier
	v_mfma_f32_16x16x32_bf16 v[126:129], v[138:141], v[170:173], v[126:129]
	v_mfma_f32_16x16x32_bf16 v[126:129], v[142:145], v[174:177], v[126:129]
	v_mfma_f32_16x16x32_bf16 v[122:125], v[150:153], v[174:177], v[122:125]
	v_mfma_f32_16x16x32_bf16 v[122:125], v[146:149], v[170:173], v[122:125]
	v_mfma_f32_16x16x32_bf16 v[110:113], v[146:149], v[178:181], v[110:113]
	v_mfma_f32_16x16x32_bf16 v[110:113], v[150:153], v[182:185], v[110:113]
	v_mfma_f32_16x16x32_bf16 v[118:121], v[142:145], v[182:185], v[118:121]
	v_mfma_f32_16x16x32_bf16 v[118:121], v[138:141], v[178:181], v[118:121]
	v_mfma_f32_16x16x32_bf16 v[102:105], v[138:141], v[186:189], v[102:105]
	v_mfma_f32_16x16x32_bf16 v[102:105], v[142:145], v[190:193], v[102:105]
	v_mfma_f32_16x16x32_bf16 v[94:97], v[150:153], v[190:193], v[94:97]
	v_mfma_f32_16x16x32_bf16 v[94:97], v[146:149], v[186:189], v[94:97]
	v_mfma_f32_16x16x32_bf16 v[78:81], v[146:149], v[202:205], v[78:81]
	v_mfma_f32_16x16x32_bf16 v[78:81], v[150:153], v[206:209], v[78:81]
	v_mfma_f32_16x16x32_bf16 v[86:89], v[142:145], v[206:209], v[86:89]
	v_mfma_f32_16x16x32_bf16 v[86:89], v[138:141], v[202:205], v[86:89]
	v_mfma_f32_16x16x32_bf16 v[114:117], v[154:157], v[170:173], v[114:117]
	v_mfma_f32_16x16x32_bf16 v[114:117], v[158:161], v[174:177], v[114:117]
	v_mfma_f32_16x16x32_bf16 v[106:109], v[166:169], v[174:177], v[106:109]
	v_mfma_f32_16x16x32_bf16 v[106:109], v[162:165], v[170:173], v[106:109]
	v_mfma_f32_16x16x32_bf16 v[90:93], v[162:165], v[178:181], v[90:93]
	v_mfma_f32_16x16x32_bf16 v[90:93], v[166:169], v[182:185], v[90:93]
	v_mfma_f32_16x16x32_bf16 v[98:101], v[158:161], v[182:185], v[98:101]
	v_mfma_f32_16x16x32_bf16 v[98:101], v[154:157], v[178:181], v[98:101]
	v_mfma_f32_16x16x32_bf16 v[82:85], v[154:157], v[186:189], v[82:85]
	v_mfma_f32_16x16x32_bf16 v[82:85], v[158:161], v[190:193], v[82:85]
	v_mfma_f32_16x16x32_bf16 v[74:77], v[166:169], v[190:193], v[74:77]
	v_mfma_f32_16x16x32_bf16 v[74:77], v[162:165], v[186:189], v[74:77]
	v_mfma_f32_16x16x32_bf16 v[66:69], v[162:165], v[202:205], v[66:69]
	v_mfma_f32_16x16x32_bf16 v[66:69], v[166:169], v[206:209], v[66:69]
	v_mfma_f32_16x16x32_bf16 v[70:73], v[158:161], v[206:209], v[70:73]
	v_mfma_f32_16x16x32_bf16 v[70:73], v[154:157], v[202:205], v[70:73]
	s_barrier
	s_setprio 0
	s_mov_b32 m0, s70
	v_lshl_add_u64 v[134:135], s[38:39], 0, v[132:133]
	ds_read_b128 v[170:173], v137 offset:16384
	ds_read_b128 v[174:177], v137 offset:17408
	ds_read_b128 v[178:181], v137 offset:18432
	ds_read_b128 v[182:185], v137 offset:19456
	ds_read_b128 v[186:189], v137 offset:20480
	ds_read_b128 v[190:193], v137 offset:21504
	ds_read_b128 v[202:205], v137 offset:22528
	ds_read_b128 v[206:209], v137 offset:23552
	global_load_lds_dwordx4 v[134:135], off
	v_lshl_add_u64 v[210:211], s[38:39], 0, v[130:131]
	s_mov_b32 m0, s67
	v_lshl_add_u64 v[212:213], s[46:47], 0, v[132:133]
	global_load_lds_dwordx4 v[210:211], off
	s_mov_b32 m0, s69
	v_lshl_add_u64 v[214:215], s[36:37], 0, v[130:131]
	global_load_lds_dwordx4 v[212:213], off
	v_lshl_add_u64 v[212:213], s[46:47], 0, v[130:131]
	s_mov_b32 m0, s68
	s_nop 0
	global_load_lds_dwordx4 v[212:213], off
	v_lshl_add_u64 v[212:213], s[36:37], 0, v[132:133]
	s_mov_b32 m0, s53
	s_nop 0
	global_load_lds_dwordx4 v[212:213], off
	s_mov_b32 m0, s56
	s_nop 0
	global_load_lds_dwordx4 v[214:215], off
	s_waitcnt vmcnt(8)
	s_waitcnt lgkmcnt(0)
	s_setprio 1
	s_barrier
	v_mfma_f32_16x16x32_bf16 v[62:65], v[138:141], v[170:173], v[62:65]
	v_mfma_f32_16x16x32_bf16 v[62:65], v[142:145], v[174:177], v[62:65]
	v_mfma_f32_16x16x32_bf16 v[58:61], v[150:153], v[174:177], v[58:61]
	v_mfma_f32_16x16x32_bf16 v[58:61], v[146:149], v[170:173], v[58:61]
	v_mfma_f32_16x16x32_bf16 v[46:49], v[146:149], v[178:181], v[46:49]
	v_mfma_f32_16x16x32_bf16 v[46:49], v[150:153], v[182:185], v[46:49]
	v_mfma_f32_16x16x32_bf16 v[54:57], v[142:145], v[182:185], v[54:57]
	v_mfma_f32_16x16x32_bf16 v[54:57], v[138:141], v[178:181], v[54:57]
	v_mfma_f32_16x16x32_bf16 v[38:41], v[138:141], v[186:189], v[38:41]
	v_mfma_f32_16x16x32_bf16 v[38:41], v[142:145], v[190:193], v[38:41]
	v_mfma_f32_16x16x32_bf16 v[30:33], v[150:153], v[190:193], v[30:33]
	v_mfma_f32_16x16x32_bf16 v[30:33], v[146:149], v[186:189], v[30:33]
	v_mfma_f32_16x16x32_bf16 v[14:17], v[146:149], v[202:205], v[14:17]
	v_mfma_f32_16x16x32_bf16 v[14:17], v[150:153], v[206:209], v[14:17]
	v_mfma_f32_16x16x32_bf16 v[22:25], v[142:145], v[206:209], v[22:25]
	v_mfma_f32_16x16x32_bf16 v[22:25], v[138:141], v[202:205], v[22:25]
	v_mfma_f32_16x16x32_bf16 v[50:53], v[154:157], v[170:173], v[50:53]
	v_mfma_f32_16x16x32_bf16 v[50:53], v[158:161], v[174:177], v[50:53]
	v_mfma_f32_16x16x32_bf16 v[42:45], v[166:169], v[174:177], v[42:45]
	v_mfma_f32_16x16x32_bf16 v[42:45], v[162:165], v[170:173], v[42:45]
	v_mfma_f32_16x16x32_bf16 v[26:29], v[162:165], v[178:181], v[26:29]
	v_mfma_f32_16x16x32_bf16 v[26:29], v[166:169], v[182:185], v[26:29]
	v_mfma_f32_16x16x32_bf16 v[34:37], v[158:161], v[182:185], v[34:37]
	v_mfma_f32_16x16x32_bf16 v[34:37], v[154:157], v[178:181], v[34:37]
	v_mfma_f32_16x16x32_bf16 v[18:21], v[154:157], v[186:189], v[18:21]
	v_mfma_f32_16x16x32_bf16 v[18:21], v[158:161], v[190:193], v[18:21]
	v_mfma_f32_16x16x32_bf16 v[10:13], v[166:169], v[190:193], v[10:13]
	v_mfma_f32_16x16x32_bf16 v[10:13], v[162:165], v[186:189], v[10:13]
	v_mfma_f32_16x16x32_bf16 v[2:5], v[162:165], v[202:205], v[2:5]
	v_mfma_f32_16x16x32_bf16 v[2:5], v[166:169], v[206:209], v[2:5]
	v_mfma_f32_16x16x32_bf16 v[6:9], v[158:161], v[206:209], v[6:9]
	v_mfma_f32_16x16x32_bf16 v[6:9], v[154:157], v[202:205], v[6:9]
	s_barrier
	s_setprio 0
	v_add_u32_e32 v150, s66, v136
	v_add_u32_e32 v166, s65, v136
	ds_read_b128 v[138:141], v150
	ds_read_b128 v[142:145], v150 offset:1024
	ds_read_b128 v[146:149], v150 offset:2048
	ds_read_b128 v[150:153], v150 offset:3072
	ds_read_b128 v[154:157], v166
	ds_read_b128 v[158:161], v166 offset:1024
	ds_read_b128 v[162:165], v166 offset:2048
	ds_read_b128 v[166:169], v166 offset:3072
	s_mov_b32 m0, s57
	v_lshl_add_u64 v[216:217], s[30:31], 0, v[132:133]
	ds_read_b128 v[170:173], v137 offset:32768
	ds_read_b128 v[174:177], v137 offset:33792
	ds_read_b128 v[178:181], v137 offset:34816
	ds_read_b128 v[182:185], v137 offset:35840
	ds_read_b128 v[186:189], v137 offset:36864
	ds_read_b128 v[190:193], v137 offset:37888
	ds_read_b128 v[202:205], v137 offset:38912
	ds_read_b128 v[206:209], v137 offset:39936
	global_load_lds_dwordx4 v[216:217], off
	v_lshl_add_u64 v[216:217], s[30:31], 0, v[130:131]
	s_mov_b32 m0, s58
	s_nop 0
	global_load_lds_dwordx4 v[216:217], off
	s_waitcnt vmcnt(8)
	s_waitcnt lgkmcnt(0)
	s_setprio 1
	s_barrier
	v_mfma_f32_16x16x32_bf16 v[126:129], v[138:141], v[170:173], v[126:129]
	v_mfma_f32_16x16x32_bf16 v[126:129], v[142:145], v[174:177], v[126:129]
	v_mfma_f32_16x16x32_bf16 v[122:125], v[150:153], v[174:177], v[122:125]
	v_mfma_f32_16x16x32_bf16 v[122:125], v[146:149], v[170:173], v[122:125]
	v_mfma_f32_16x16x32_bf16 v[110:113], v[146:149], v[178:181], v[110:113]
	v_mfma_f32_16x16x32_bf16 v[110:113], v[150:153], v[182:185], v[110:113]
	v_mfma_f32_16x16x32_bf16 v[118:121], v[142:145], v[182:185], v[118:121]
	v_mfma_f32_16x16x32_bf16 v[118:121], v[138:141], v[178:181], v[118:121]
	v_mfma_f32_16x16x32_bf16 v[102:105], v[138:141], v[186:189], v[102:105]
	v_mfma_f32_16x16x32_bf16 v[102:105], v[142:145], v[190:193], v[102:105]
	v_mfma_f32_16x16x32_bf16 v[94:97], v[150:153], v[190:193], v[94:97]
	v_mfma_f32_16x16x32_bf16 v[94:97], v[146:149], v[186:189], v[94:97]
	v_mfma_f32_16x16x32_bf16 v[78:81], v[146:149], v[202:205], v[78:81]
	v_mfma_f32_16x16x32_bf16 v[78:81], v[150:153], v[206:209], v[78:81]
	v_mfma_f32_16x16x32_bf16 v[86:89], v[142:145], v[206:209], v[86:89]
	v_mfma_f32_16x16x32_bf16 v[86:89], v[138:141], v[202:205], v[86:89]
	v_mfma_f32_16x16x32_bf16 v[114:117], v[154:157], v[170:173], v[114:117]
	v_mfma_f32_16x16x32_bf16 v[114:117], v[158:161], v[174:177], v[114:117]
	v_mfma_f32_16x16x32_bf16 v[106:109], v[166:169], v[174:177], v[106:109]
	v_mfma_f32_16x16x32_bf16 v[106:109], v[162:165], v[170:173], v[106:109]
	v_mfma_f32_16x16x32_bf16 v[90:93], v[162:165], v[178:181], v[90:93]
	v_mfma_f32_16x16x32_bf16 v[90:93], v[166:169], v[182:185], v[90:93]
	v_mfma_f32_16x16x32_bf16 v[98:101], v[158:161], v[182:185], v[98:101]
	v_mfma_f32_16x16x32_bf16 v[98:101], v[154:157], v[178:181], v[98:101]
	v_mfma_f32_16x16x32_bf16 v[82:85], v[154:157], v[186:189], v[82:85]
	v_mfma_f32_16x16x32_bf16 v[82:85], v[158:161], v[190:193], v[82:85]
	v_mfma_f32_16x16x32_bf16 v[74:77], v[166:169], v[190:193], v[74:77]
	v_mfma_f32_16x16x32_bf16 v[74:77], v[162:165], v[186:189], v[74:77]
	v_mfma_f32_16x16x32_bf16 v[66:69], v[162:165], v[202:205], v[66:69]
	v_mfma_f32_16x16x32_bf16 v[66:69], v[166:169], v[206:209], v[66:69]
	v_mfma_f32_16x16x32_bf16 v[70:73], v[158:161], v[206:209], v[70:73]
	v_mfma_f32_16x16x32_bf16 v[70:73], v[154:157], v[202:205], v[70:73]
	s_barrier
	s_setprio 0
	s_mov_b32 m0, s64
	v_lshl_add_u64 v[134:135], v[134:135], 0, s[10:11]
	ds_read_b128 v[170:173], v137 offset:49152
	ds_read_b128 v[174:177], v137 offset:50176
	ds_read_b128 v[178:181], v137 offset:51200
	ds_read_b128 v[182:185], v137 offset:52224
	ds_read_b128 v[186:189], v137 offset:53248
	ds_read_b128 v[190:193], v137 offset:54272
	ds_read_b128 v[202:205], v137 offset:55296
	ds_read_b128 v[206:209], v137 offset:56320
	global_load_lds_dwordx4 v[134:135], off
	v_lshl_add_u64 v[134:135], v[210:211], 0, s[10:11]
	s_mov_b32 m0, s21
	s_nop 0
	global_load_lds_dwordx4 v[134:135], off
	v_lshl_add_u64 v[134:135], s[28:29], 0, v[132:133]
	s_mov_b32 m0, s72
	s_nop 0
	global_load_lds_dwordx4 v[134:135], off
	v_lshl_add_u64 v[134:135], s[28:29], 0, v[130:131]
	s_mov_b32 m0, s71
	s_nop 0
	global_load_lds_dwordx4 v[134:135], off
	v_lshl_add_u64 v[134:135], v[212:213], 0, s[10:11]
	s_mov_b32 m0, s59
	s_nop 0
	global_load_lds_dwordx4 v[134:135], off
	v_lshl_add_u64 v[134:135], v[214:215], 0, s[10:11]
	s_mov_b32 m0, s60
	s_nop 0
	global_load_lds_dwordx4 v[134:135], off
	s_waitcnt vmcnt(8)
	s_waitcnt lgkmcnt(0)
	s_setprio 1
	s_barrier
	v_mfma_f32_16x16x32_bf16 v[62:65], v[138:141], v[170:173], v[62:65]
	v_mfma_f32_16x16x32_bf16 v[62:65], v[142:145], v[174:177], v[62:65]
	v_mfma_f32_16x16x32_bf16 v[58:61], v[150:153], v[174:177], v[58:61]
	v_mfma_f32_16x16x32_bf16 v[58:61], v[146:149], v[170:173], v[58:61]
	v_mfma_f32_16x16x32_bf16 v[46:49], v[146:149], v[178:181], v[46:49]
	v_mfma_f32_16x16x32_bf16 v[46:49], v[150:153], v[182:185], v[46:49]
	v_mfma_f32_16x16x32_bf16 v[54:57], v[142:145], v[182:185], v[54:57]
	v_mfma_f32_16x16x32_bf16 v[54:57], v[138:141], v[178:181], v[54:57]
	v_mfma_f32_16x16x32_bf16 v[38:41], v[138:141], v[186:189], v[38:41]
	v_mfma_f32_16x16x32_bf16 v[38:41], v[142:145], v[190:193], v[38:41]
	v_mfma_f32_16x16x32_bf16 v[30:33], v[150:153], v[190:193], v[30:33]
	v_mfma_f32_16x16x32_bf16 v[30:33], v[146:149], v[186:189], v[30:33]
	v_mfma_f32_16x16x32_bf16 v[14:17], v[146:149], v[202:205], v[14:17]
	v_mfma_f32_16x16x32_bf16 v[14:17], v[150:153], v[206:209], v[14:17]
	v_mfma_f32_16x16x32_bf16 v[22:25], v[142:145], v[206:209], v[22:25]
	v_mfma_f32_16x16x32_bf16 v[22:25], v[138:141], v[202:205], v[22:25]
	v_mfma_f32_16x16x32_bf16 v[50:53], v[154:157], v[170:173], v[50:53]
	v_mfma_f32_16x16x32_bf16 v[50:53], v[158:161], v[174:177], v[50:53]
	v_mfma_f32_16x16x32_bf16 v[42:45], v[166:169], v[174:177], v[42:45]
	v_mfma_f32_16x16x32_bf16 v[42:45], v[162:165], v[170:173], v[42:45]
	v_mfma_f32_16x16x32_bf16 v[26:29], v[162:165], v[178:181], v[26:29]
	v_mfma_f32_16x16x32_bf16 v[26:29], v[166:169], v[182:185], v[26:29]
	v_mfma_f32_16x16x32_bf16 v[34:37], v[158:161], v[182:185], v[34:37]
	v_mfma_f32_16x16x32_bf16 v[34:37], v[154:157], v[178:181], v[34:37]
	v_mfma_f32_16x16x32_bf16 v[18:21], v[154:157], v[186:189], v[18:21]
	v_mfma_f32_16x16x32_bf16 v[18:21], v[158:161], v[190:193], v[18:21]
	v_mfma_f32_16x16x32_bf16 v[10:13], v[166:169], v[190:193], v[10:13]
	v_mfma_f32_16x16x32_bf16 v[10:13], v[162:165], v[186:189], v[10:13]
	v_mfma_f32_16x16x32_bf16 v[2:5], v[162:165], v[202:205], v[2:5]
	v_mfma_f32_16x16x32_bf16 v[2:5], v[166:169], v[206:209], v[2:5]
	v_mfma_f32_16x16x32_bf16 v[6:9], v[158:161], v[206:209], v[6:9]
	v_mfma_f32_16x16x32_bf16 v[6:9], v[154:157], v[202:205], v[6:9]
	s_barrier
	s_setprio 0
	s_andn2_b64 vcc, exec, s[26:27]
	s_mov_b64 s[28:29], -1
	s_mov_b64 s[26:27], 0
	s_movk_i32 s21, 0x100
	s_cbranch_vccz .LBB0_1002
	s_and_b64 vcc, exec, s[16:17]
	s_cbranch_vccz .LBB0_1005
	s_barrier

.LBB0_1087:
	s_add_u32 s30, s28, 0xfff80080
	s_addc_u32 s31, s29, -1
	s_cmp_eq_u32 s83, 28
	s_cselect_b32 s43, s23, s31
	s_cselect_b32 s42, s44, s30
	s_cselect_b32 s31, s21, s82
	s_cselect_b32 s30, s45, s81
	s_add_i32 s84, 0, 0x10000
	s_add_i32 s86, 0, 0x14000
	v_add_u32_e32 v62, s84, v229
	v_add_u32_e32 v158, s86, v229
	ds_read_b128 v[42:45], v62
	ds_read_b128 v[46:49], v62 offset:1024
	ds_read_b128 v[58:61], v62 offset:2048
	ds_read_b128 v[62:65], v62 offset:3072
	ds_read_b128 v[146:149], v158
	ds_read_b128 v[150:153], v158 offset:1024
	ds_read_b128 v[154:157], v158 offset:2048
	ds_read_b128 v[158:161], v158 offset:3072
	v_lshl_add_u64 v[208:209], s[28:29], 0, v[204:205]
	s_add_i32 m0, s71, 0xc000
	ds_read_b128 v[162:165], v230
	ds_read_b128 v[166:169], v230 offset:1024
	ds_read_b128 v[170:173], v230 offset:2048
	ds_read_b128 v[174:177], v230 offset:3072
	ds_read_b128 v[178:181], v230 offset:4096
	ds_read_b128 v[182:185], v230 offset:5120
	ds_read_b128 v[186:189], v230 offset:6144
	ds_read_b128 v[190:193], v230 offset:7168
	global_load_lds_dwordx4 v[208:209], off
	v_lshl_add_u64 v[208:209], s[28:29], 0, v[206:207]
	s_add_i32 m0, s71, 0xe000
	s_nop 0
	global_load_lds_dwordx4 v[208:209], off
	s_waitcnt vmcnt(8)
	s_waitcnt lgkmcnt(0)
	s_setprio 1
	s_barrier
	v_mfma_f32_16x16x32_bf16 v[142:145], v[42:45], v[162:165], v[142:145]
	v_mfma_f32_16x16x32_bf16 v[142:145], v[46:49], v[166:169], v[142:145]
	v_mfma_f32_16x16x32_bf16 v[138:141], v[62:65], v[166:169], v[138:141]
	v_mfma_f32_16x16x32_bf16 v[138:141], v[58:61], v[162:165], v[138:141]
	v_mfma_f32_16x16x32_bf16 v[122:125], v[58:61], v[170:173], v[122:125]
	v_mfma_f32_16x16x32_bf16 v[122:125], v[62:65], v[174:177], v[122:125]
	v_mfma_f32_16x16x32_bf16 v[126:129], v[46:49], v[174:177], v[126:129]
	v_mfma_f32_16x16x32_bf16 v[126:129], v[42:45], v[170:173], v[126:129]
	v_mfma_f32_16x16x32_bf16 v[110:113], v[42:45], v[178:181], v[110:113]
	v_mfma_f32_16x16x32_bf16 v[110:113], v[46:49], v[182:185], v[110:113]
	v_mfma_f32_16x16x32_bf16 v[106:109], v[62:65], v[182:185], v[106:109]
	v_mfma_f32_16x16x32_bf16 v[106:109], v[58:61], v[178:181], v[106:109]
	v_mfma_f32_16x16x32_bf16 v[90:93], v[58:61], v[186:189], v[90:93]
	v_mfma_f32_16x16x32_bf16 v[90:93], v[62:65], v[190:193], v[90:93]
	v_mfma_f32_16x16x32_bf16 v[94:97], v[46:49], v[190:193], v[94:97]
	v_mfma_f32_16x16x32_bf16 v[94:97], v[42:45], v[186:189], v[94:97]
	v_mfma_f32_16x16x32_bf16 v[134:137], v[146:149], v[162:165], v[134:137]
	v_mfma_f32_16x16x32_bf16 v[134:137], v[150:153], v[166:169], v[134:137]
	v_mfma_f32_16x16x32_bf16 v[130:133], v[158:161], v[166:169], v[130:133]
	v_mfma_f32_16x16x32_bf16 v[130:133], v[154:157], v[162:165], v[130:133]
	v_mfma_f32_16x16x32_bf16 v[114:117], v[154:157], v[170:173], v[114:117]
	v_mfma_f32_16x16x32_bf16 v[114:117], v[158:161], v[174:177], v[114:117]
	v_mfma_f32_16x16x32_bf16 v[118:121], v[150:153], v[174:177], v[118:121]
	v_mfma_f32_16x16x32_bf16 v[118:121], v[146:149], v[170:173], v[118:121]
	v_mfma_f32_16x16x32_bf16 v[102:105], v[146:149], v[178:181], v[102:105]
	v_mfma_f32_16x16x32_bf16 v[102:105], v[150:153], v[182:185], v[102:105]
	v_mfma_f32_16x16x32_bf16 v[98:101], v[158:161], v[182:185], v[98:101]
	v_mfma_f32_16x16x32_bf16 v[98:101], v[154:157], v[178:181], v[98:101]
	v_mfma_f32_16x16x32_bf16 v[82:85], v[154:157], v[186:189], v[82:85]
	v_mfma_f32_16x16x32_bf16 v[82:85], v[158:161], v[190:193], v[82:85]
	v_mfma_f32_16x16x32_bf16 v[86:89], v[150:153], v[190:193], v[86:89]
	v_mfma_f32_16x16x32_bf16 v[86:89], v[146:149], v[186:189], v[86:89]
	s_barrier
	s_setprio 0
	s_add_i32 s84, s84, s70
	v_lshl_add_u64 v[208:209], s[30:31], 0, v[194:195]
	s_mov_b32 m0, s84
	ds_read_b128 v[162:165], v230 offset:16384
	ds_read_b128 v[166:169], v230 offset:17408
	ds_read_b128 v[170:173], v230 offset:18432
	ds_read_b128 v[174:177], v230 offset:19456
	ds_read_b128 v[178:181], v230 offset:20480
	ds_read_b128 v[182:185], v230 offset:21504
	ds_read_b128 v[186:189], v230 offset:22528
	ds_read_b128 v[190:193], v230 offset:23552
	global_load_lds_dwordx4 v[208:209], off
	s_add_i32 m0, s84, 0x2000
	s_add_u32 s84, s30, 0x80000
	v_lshl_add_u64 v[210:211], s[30:31], 0, v[202:203]
	s_addc_u32 s85, s31, 0
	s_add_i32 s86, s86, s70
	global_load_lds_dwordx4 v[210:211], off
	v_lshl_add_u64 v[212:213], s[84:85], 0, v[194:195]
	s_mov_b32 m0, s86
	v_lshl_add_u64 v[214:215], s[42:43], 0, v[202:203]
	global_load_lds_dwordx4 v[212:213], off
	v_lshl_add_u64 v[212:213], s[84:85], 0, v[202:203]
	s_add_i32 m0, s86, 0x2000
	s_nop 0
	global_load_lds_dwordx4 v[212:213], off
	v_lshl_add_u64 v[212:213], s[42:43], 0, v[194:195]
	s_mov_b32 m0, s71
	s_nop 0
	global_load_lds_dwordx4 v[212:213], off
	s_mov_b32 m0, s72
	s_nop 0
	global_load_lds_dwordx4 v[214:215], off
	s_waitcnt vmcnt(8)
	s_waitcnt lgkmcnt(0)
	s_setprio 1
	s_barrier
	v_mfma_f32_16x16x32_bf16 v[78:81], v[42:45], v[162:165], v[78:81]
	v_mfma_f32_16x16x32_bf16 v[78:81], v[46:49], v[166:169], v[78:81]
	v_mfma_f32_16x16x32_bf16 v[74:77], v[62:65], v[166:169], v[74:77]
	v_mfma_f32_16x16x32_bf16 v[74:77], v[58:61], v[162:165], v[74:77]
	v_mfma_f32_16x16x32_bf16 v[50:53], v[58:61], v[170:173], v[50:53]
	v_mfma_f32_16x16x32_bf16 v[50:53], v[62:65], v[174:177], v[50:53]
	v_mfma_f32_16x16x32_bf16 v[54:57], v[46:49], v[174:177], v[54:57]
	v_mfma_f32_16x16x32_bf16 v[54:57], v[42:45], v[170:173], v[54:57]
	v_mfma_f32_16x16x32_bf16 v[30:33], v[42:45], v[178:181], v[30:33]
	v_mfma_f32_16x16x32_bf16 v[30:33], v[46:49], v[182:185], v[30:33]
	v_mfma_f32_16x16x32_bf16 v[26:29], v[62:65], v[182:185], v[26:29]
	v_mfma_f32_16x16x32_bf16 v[26:29], v[58:61], v[178:181], v[26:29]
	v_mfma_f32_16x16x32_bf16 v[10:13], v[58:61], v[186:189], v[10:13]
	v_mfma_f32_16x16x32_bf16 v[10:13], v[62:65], v[190:193], v[10:13]
	v_mfma_f32_16x16x32_bf16 v[14:17], v[46:49], v[190:193], v[14:17]
	v_mfma_f32_16x16x32_bf16 v[14:17], v[42:45], v[186:189], v[14:17]
	v_mfma_f32_16x16x32_bf16 v[38:41], v[146:149], v[170:173], v[38:41]
	v_mfma_f32_16x16x32_bf16 v[34:37], v[154:157], v[170:173], v[34:37]
	v_mfma_f32_16x16x32_bf16 v[22:25], v[146:149], v[178:181], v[22:25]
	v_mfma_f32_16x16x32_bf16 v[18:21], v[154:157], v[178:181], v[18:21]
	v_mfma_f32_16x16x32_bf16 v[6:9], v[146:149], v[186:189], v[6:9]
	v_mfma_f32_16x16x32_bf16 v[2:5], v[154:157], v[186:189], v[2:5]
	v_mfma_f32_16x16x32_bf16 v[42:45], v[146:149], v[162:165], v[70:73]
	v_mfma_f32_16x16x32_bf16 v[46:49], v[154:157], v[162:165], v[66:69]
	v_mfma_f32_16x16x32_bf16 v[38:41], v[150:153], v[174:177], v[38:41]
	v_mfma_f32_16x16x32_bf16 v[34:37], v[158:161], v[174:177], v[34:37]
	v_mfma_f32_16x16x32_bf16 v[22:25], v[150:153], v[182:185], v[22:25]
	v_mfma_f32_16x16x32_bf16 v[18:21], v[158:161], v[182:185], v[18:21]
	v_mfma_f32_16x16x32_bf16 v[6:9], v[150:153], v[190:193], v[6:9]
	v_mfma_f32_16x16x32_bf16 v[2:5], v[158:161], v[190:193], v[2:5]
	v_mfma_f32_16x16x32_bf16 v[42:45], v[150:153], v[166:169], v[42:45]
	v_mfma_f32_16x16x32_bf16 v[46:49], v[158:161], v[166:169], v[46:49]
	s_barrier
	s_setprio 0
	s_add_i32 s84, 0, 0x18000
	s_add_i32 s85, 0, 0x1c000
	v_add_u32_e32 v70, s84, v229
	v_add_u32_e32 v158, s85, v229
	ds_read_b128 v[58:61], v70
	ds_read_b128 v[62:65], v70 offset:1024
	ds_read_b128 v[66:69], v70 offset:2048
	ds_read_b128 v[70:73], v70 offset:3072
	ds_read_b128 v[146:149], v158
	ds_read_b128 v[150:153], v158 offset:1024
	ds_read_b128 v[154:157], v158 offset:2048
	ds_read_b128 v[158:161], v158 offset:3072
	s_add_u32 s42, s42, 0x80000
	s_addc_u32 s43, s43, 0
	s_mov_b32 m0, s73
	v_lshl_add_u64 v[216:217], s[42:43], 0, v[194:195]
	ds_read_b128 v[162:165], v230 offset:32768
	ds_read_b128 v[166:169], v230 offset:33792
	ds_read_b128 v[170:173], v230 offset:34816
	ds_read_b128 v[174:177], v230 offset:35840
	ds_read_b128 v[178:181], v230 offset:36864
	ds_read_b128 v[182:185], v230 offset:37888
	ds_read_b128 v[186:189], v230 offset:38912
	ds_read_b128 v[190:193], v230 offset:39936
	global_load_lds_dwordx4 v[216:217], off
	v_lshl_add_u64 v[216:217], s[42:43], 0, v[202:203]
	s_mov_b32 m0, s74
	s_nop 0
	global_load_lds_dwordx4 v[216:217], off
	s_waitcnt vmcnt(8)
	s_waitcnt lgkmcnt(0)
	s_setprio 1
	s_barrier
	v_mfma_f32_16x16x32_bf16 v[142:145], v[58:61], v[162:165], v[142:145]
	v_mfma_f32_16x16x32_bf16 v[142:145], v[62:65], v[166:169], v[142:145]
	v_mfma_f32_16x16x32_bf16 v[138:141], v[70:73], v[166:169], v[138:141]
	v_mfma_f32_16x16x32_bf16 v[138:141], v[66:69], v[162:165], v[138:141]
	v_mfma_f32_16x16x32_bf16 v[122:125], v[66:69], v[170:173], v[122:125]
	v_mfma_f32_16x16x32_bf16 v[122:125], v[70:73], v[174:177], v[122:125]
	v_mfma_f32_16x16x32_bf16 v[126:129], v[62:65], v[174:177], v[126:129]
	v_mfma_f32_16x16x32_bf16 v[126:129], v[58:61], v[170:173], v[126:129]
	v_mfma_f32_16x16x32_bf16 v[110:113], v[58:61], v[178:181], v[110:113]
	v_mfma_f32_16x16x32_bf16 v[110:113], v[62:65], v[182:185], v[110:113]
	v_mfma_f32_16x16x32_bf16 v[106:109], v[70:73], v[182:185], v[106:109]
	v_mfma_f32_16x16x32_bf16 v[106:109], v[66:69], v[178:181], v[106:109]
	v_mfma_f32_16x16x32_bf16 v[90:93], v[66:69], v[186:189], v[90:93]
	v_mfma_f32_16x16x32_bf16 v[90:93], v[70:73], v[190:193], v[90:93]
	v_mfma_f32_16x16x32_bf16 v[94:97], v[62:65], v[190:193], v[94:97]
	v_mfma_f32_16x16x32_bf16 v[94:97], v[58:61], v[186:189], v[94:97]
	v_mfma_f32_16x16x32_bf16 v[134:137], v[146:149], v[162:165], v[134:137]
	v_mfma_f32_16x16x32_bf16 v[134:137], v[150:153], v[166:169], v[134:137]
	v_mfma_f32_16x16x32_bf16 v[130:133], v[158:161], v[166:169], v[130:133]
	v_mfma_f32_16x16x32_bf16 v[130:133], v[154:157], v[162:165], v[130:133]
	v_mfma_f32_16x16x32_bf16 v[114:117], v[154:157], v[170:173], v[114:117]
	v_mfma_f32_16x16x32_bf16 v[114:117], v[158:161], v[174:177], v[114:117]
	v_mfma_f32_16x16x32_bf16 v[118:121], v[150:153], v[174:177], v[118:121]
	v_mfma_f32_16x16x32_bf16 v[118:121], v[146:149], v[170:173], v[118:121]
	v_mfma_f32_16x16x32_bf16 v[102:105], v[146:149], v[178:181], v[102:105]
	v_mfma_f32_16x16x32_bf16 v[102:105], v[150:153], v[182:185], v[102:105]
	v_mfma_f32_16x16x32_bf16 v[98:101], v[158:161], v[182:185], v[98:101]
	v_mfma_f32_16x16x32_bf16 v[98:101], v[154:157], v[178:181], v[98:101]
	v_mfma_f32_16x16x32_bf16 v[82:85], v[154:157], v[186:189], v[82:85]
	v_mfma_f32_16x16x32_bf16 v[82:85], v[158:161], v[190:193], v[82:85]
	v_mfma_f32_16x16x32_bf16 v[86:89], v[150:153], v[190:193], v[86:89]
	v_mfma_f32_16x16x32_bf16 v[86:89], v[146:149], v[186:189], v[86:89]
	s_barrier
	s_setprio 0
	s_add_i32 s42, s84, s70
	v_lshl_add_u64 v[208:209], v[208:209], 0, s[10:11]
	s_mov_b32 m0, s42
	ds_read_b128 v[162:165], v230 offset:49152
	ds_read_b128 v[166:169], v230 offset:50176
	ds_read_b128 v[170:173], v230 offset:51200
	ds_read_b128 v[174:177], v230 offset:52224
	ds_read_b128 v[178:181], v230 offset:53248
	ds_read_b128 v[182:185], v230 offset:54272
	ds_read_b128 v[186:189], v230 offset:55296
	ds_read_b128 v[190:193], v230 offset:56320
	global_load_lds_dwordx4 v[208:209], off
	s_add_i32 m0, s42, 0x2000
	s_add_u32 s30, s30, 0x80080
	v_lshl_add_u64 v[208:209], v[210:211], 0, s[10:11]
	s_addc_u32 s31, s31, 0
	s_add_i32 s42, s85, s70
	global_load_lds_dwordx4 v[208:209], off
	v_lshl_add_u64 v[208:209], s[30:31], 0, v[194:195]
	s_mov_b32 m0, s42
	s_nop 0
	global_load_lds_dwordx4 v[208:209], off
	v_lshl_add_u64 v[208:209], s[30:31], 0, v[202:203]
	s_add_i32 m0, s42, 0x2000
	s_nop 0
	global_load_lds_dwordx4 v[208:209], off
	v_lshl_add_u64 v[208:209], v[212:213], 0, s[10:11]
	s_mov_b32 m0, s79
	s_nop 0
	global_load_lds_dwordx4 v[208:209], off
	v_lshl_add_u64 v[208:209], v[214:215], 0, s[10:11]
	s_mov_b32 m0, s80
	s_nop 0
	global_load_lds_dwordx4 v[208:209], off
	s_waitcnt vmcnt(8)
	s_waitcnt lgkmcnt(0)
	s_setprio 1
	s_barrier
	v_mfma_f32_16x16x32_bf16 v[78:81], v[58:61], v[162:165], v[78:81]
	v_mfma_f32_16x16x32_bf16 v[78:81], v[62:65], v[166:169], v[78:81]
	v_mfma_f32_16x16x32_bf16 v[74:77], v[70:73], v[166:169], v[74:77]
	v_mfma_f32_16x16x32_bf16 v[74:77], v[66:69], v[162:165], v[74:77]
	v_mfma_f32_16x16x32_bf16 v[50:53], v[66:69], v[170:173], v[50:53]
	v_mfma_f32_16x16x32_bf16 v[50:53], v[70:73], v[174:177], v[50:53]
	v_mfma_f32_16x16x32_bf16 v[54:57], v[62:65], v[174:177], v[54:57]
	v_mfma_f32_16x16x32_bf16 v[54:57], v[58:61], v[170:173], v[54:57]
	v_mfma_f32_16x16x32_bf16 v[30:33], v[58:61], v[178:181], v[30:33]
	v_mfma_f32_16x16x32_bf16 v[30:33], v[62:65], v[182:185], v[30:33]
	v_mfma_f32_16x16x32_bf16 v[26:29], v[70:73], v[182:185], v[26:29]
	v_mfma_f32_16x16x32_bf16 v[26:29], v[66:69], v[178:181], v[26:29]
	v_mfma_f32_16x16x32_bf16 v[10:13], v[66:69], v[186:189], v[10:13]
	v_mfma_f32_16x16x32_bf16 v[10:13], v[70:73], v[190:193], v[10:13]
	v_mfma_f32_16x16x32_bf16 v[14:17], v[62:65], v[190:193], v[14:17]
	v_mfma_f32_16x16x32_bf16 v[14:17], v[58:61], v[186:189], v[14:17]
	v_mfma_f32_16x16x32_bf16 v[42:45], v[146:149], v[162:165], v[42:45]
	v_mfma_f32_16x16x32_bf16 v[70:73], v[150:153], v[166:169], v[42:45]
	v_mfma_f32_16x16x32_bf16 v[42:45], v[154:157], v[162:165], v[46:49]
	v_mfma_f32_16x16x32_bf16 v[38:41], v[146:149], v[170:173], v[38:41]
	v_mfma_f32_16x16x32_bf16 v[34:37], v[154:157], v[170:173], v[34:37]
	v_mfma_f32_16x16x32_bf16 v[22:25], v[146:149], v[178:181], v[22:25]
	v_mfma_f32_16x16x32_bf16 v[18:21], v[154:157], v[178:181], v[18:21]
	v_mfma_f32_16x16x32_bf16 v[6:9], v[146:149], v[186:189], v[6:9]
	v_mfma_f32_16x16x32_bf16 v[2:5], v[154:157], v[186:189], v[2:5]
	v_mfma_f32_16x16x32_bf16 v[66:69], v[158:161], v[166:169], v[42:45]
	v_mfma_f32_16x16x32_bf16 v[38:41], v[150:153], v[174:177], v[38:41]
	v_mfma_f32_16x16x32_bf16 v[34:37], v[158:161], v[174:177], v[34:37]
	v_mfma_f32_16x16x32_bf16 v[22:25], v[150:153], v[182:185], v[22:25]
	v_mfma_f32_16x16x32_bf16 v[18:21], v[158:161], v[182:185], v[18:21]
	v_mfma_f32_16x16x32_bf16 v[6:9], v[150:153], v[190:193], v[6:9]
	v_mfma_f32_16x16x32_bf16 v[2:5], v[158:161], v[190:193], v[2:5]
	s_barrier
	s_setprio 0
	s_add_i32 s83, s83, 2
	s_add_u32 s28, s28, 0x100
	s_addc_u32 s29, s29, 0
	s_add_u32 s81, s81, 0x100
	s_addc_u32 s82, s82, 0
	s_cmp_gt_u32 s83, 29
	s_cbranch_scc0 .LBB0_1087
	s_and_b64 vcc, exec, s[16:17]
	s_cbranch_vccz .LBB0_1090
	s_barrier

.LBB0_1272:
	s_add_u32 s30, s28, 0xfff80080
	s_addc_u32 s31, s29, -1
	s_add_i32 s66, 0, 0x10000
	s_cmp_eq_u32 s65, 28
	s_cselect_b32 s37, s60, s31
	s_cselect_b32 s36, s61, s30
	s_cselect_b32 s31, s21, s64
	s_cselect_b32 s30, s62, s63
	s_add_i32 s68, 0, 0x14000
	v_add_u32_e32 v126, s66, v156
	v_add_u32_e32 v154, s68, v156
	ds_read_b128 v[114:117], v126
	ds_read_b128 v[118:121], v126 offset:1024
	ds_read_b128 v[122:125], v126 offset:2048
	ds_read_b128 v[126:129], v126 offset:3072
	ds_read_b128 v[158:161], v154
	ds_read_b128 v[162:165], v154 offset:1024
	ds_read_b128 v[166:169], v154 offset:2048
	ds_read_b128 v[170:173], v154 offset:3072
	v_lshl_add_u64 v[154:155], s[28:29], 0, v[150:151]
	s_add_i32 m0, s49, 0xc000
	ds_read_b128 v[174:177], v157
	ds_read_b128 v[178:181], v157 offset:1024
	ds_read_b128 v[182:185], v157 offset:2048
	ds_read_b128 v[186:189], v157 offset:3072
	ds_read_b128 v[190:193], v157 offset:4096
	ds_read_b128 v[202:205], v157 offset:5120
	ds_read_b128 v[206:209], v157 offset:6144
	ds_read_b128 v[210:213], v157 offset:7168
	global_load_lds_dwordx4 v[154:155], off
	v_lshl_add_u64 v[154:155], s[28:29], 0, v[152:153]
	s_add_i32 m0, s49, 0xe000
	s_nop 0
	global_load_lds_dwordx4 v[154:155], off
	s_waitcnt vmcnt(8)
	s_waitcnt lgkmcnt(0)
	s_setprio 1
	s_barrier
	v_mfma_f32_16x16x32_bf16 v[142:145], v[114:117], v[174:177], v[142:145]
	v_mfma_f32_16x16x32_bf16 v[142:145], v[118:121], v[178:181], v[142:145]
	v_mfma_f32_16x16x32_bf16 v[138:141], v[126:129], v[178:181], v[138:141]
	v_mfma_f32_16x16x32_bf16 v[138:141], v[122:125], v[174:177], v[138:141]
	v_mfma_f32_16x16x32_bf16 v[106:109], v[122:125], v[182:185], v[106:109]
	v_mfma_f32_16x16x32_bf16 v[106:109], v[126:129], v[186:189], v[106:109]
	v_mfma_f32_16x16x32_bf16 v[110:113], v[118:121], v[186:189], v[110:113]
	v_mfma_f32_16x16x32_bf16 v[110:113], v[114:117], v[182:185], v[110:113]
	v_mfma_f32_16x16x32_bf16 v[94:97], v[114:117], v[190:193], v[94:97]
	v_mfma_f32_16x16x32_bf16 v[94:97], v[118:121], v[202:205], v[94:97]
	v_mfma_f32_16x16x32_bf16 v[90:93], v[126:129], v[202:205], v[90:93]
	v_mfma_f32_16x16x32_bf16 v[90:93], v[122:125], v[190:193], v[90:93]
	v_mfma_f32_16x16x32_bf16 v[74:77], v[122:125], v[206:209], v[74:77]
	v_mfma_f32_16x16x32_bf16 v[74:77], v[126:129], v[210:213], v[74:77]
	v_mfma_f32_16x16x32_bf16 v[78:81], v[118:121], v[210:213], v[78:81]
	v_mfma_f32_16x16x32_bf16 v[78:81], v[114:117], v[206:209], v[78:81]
	v_mfma_f32_16x16x32_bf16 v[134:137], v[158:161], v[174:177], v[134:137]
	v_mfma_f32_16x16x32_bf16 v[134:137], v[162:165], v[178:181], v[134:137]
	v_mfma_f32_16x16x32_bf16 v[130:133], v[170:173], v[178:181], v[130:133]
	v_mfma_f32_16x16x32_bf16 v[130:133], v[166:169], v[174:177], v[130:133]
	v_mfma_f32_16x16x32_bf16 v[98:101], v[166:169], v[182:185], v[98:101]
	v_mfma_f32_16x16x32_bf16 v[98:101], v[170:173], v[186:189], v[98:101]
	v_mfma_f32_16x16x32_bf16 v[102:105], v[162:165], v[186:189], v[102:105]
	v_mfma_f32_16x16x32_bf16 v[102:105], v[158:161], v[182:185], v[102:105]
	v_mfma_f32_16x16x32_bf16 v[86:89], v[158:161], v[190:193], v[86:89]
	v_mfma_f32_16x16x32_bf16 v[86:89], v[162:165], v[202:205], v[86:89]
	v_mfma_f32_16x16x32_bf16 v[82:85], v[170:173], v[202:205], v[82:85]
	v_mfma_f32_16x16x32_bf16 v[82:85], v[166:169], v[190:193], v[82:85]
	v_mfma_f32_16x16x32_bf16 v[66:69], v[166:169], v[206:209], v[66:69]
	v_mfma_f32_16x16x32_bf16 v[66:69], v[170:173], v[210:213], v[66:69]
	v_mfma_f32_16x16x32_bf16 v[70:73], v[162:165], v[210:213], v[70:73]
	v_mfma_f32_16x16x32_bf16 v[70:73], v[158:161], v[206:209], v[70:73]
	s_barrier
	s_setprio 0
	s_add_i32 s66, s66, s48
	v_lshl_add_u64 v[154:155], s[30:31], 0, v[146:147]
	s_mov_b32 m0, s66
	ds_read_b128 v[174:177], v157 offset:16384
	ds_read_b128 v[178:181], v157 offset:17408
	ds_read_b128 v[182:185], v157 offset:18432
	ds_read_b128 v[186:189], v157 offset:19456
	ds_read_b128 v[190:193], v157 offset:20480
	ds_read_b128 v[202:205], v157 offset:21504
	ds_read_b128 v[206:209], v157 offset:22528
	ds_read_b128 v[210:213], v157 offset:23552
	global_load_lds_dwordx4 v[154:155], off
	s_add_i32 m0, s66, 0x2000
	s_add_u32 s66, s30, 0x80000
	v_lshl_add_u64 v[214:215], s[30:31], 0, v[148:149]
	s_addc_u32 s67, s31, 0
	s_add_i32 s68, s68, s48
	global_load_lds_dwordx4 v[214:215], off
	v_lshl_add_u64 v[216:217], s[66:67], 0, v[146:147]
	s_mov_b32 m0, s68
	v_lshl_add_u64 v[228:229], s[36:37], 0, v[148:149]
	global_load_lds_dwordx4 v[216:217], off
	v_lshl_add_u64 v[216:217], s[66:67], 0, v[148:149]
	s_add_i32 m0, s68, 0x2000
	s_nop 0
	global_load_lds_dwordx4 v[216:217], off
	v_lshl_add_u64 v[216:217], s[36:37], 0, v[146:147]
	s_mov_b32 m0, s49
	s_nop 0
	global_load_lds_dwordx4 v[216:217], off
	s_mov_b32 m0, s50
	s_nop 0
	global_load_lds_dwordx4 v[228:229], off
	s_waitcnt vmcnt(8)
	s_waitcnt lgkmcnt(0)
	s_setprio 1
	s_barrier
	v_mfma_f32_16x16x32_bf16 v[62:65], v[114:117], v[174:177], v[62:65]
	v_mfma_f32_16x16x32_bf16 v[62:65], v[118:121], v[178:181], v[62:65]
	v_mfma_f32_16x16x32_bf16 v[58:61], v[126:129], v[178:181], v[58:61]
	v_mfma_f32_16x16x32_bf16 v[58:61], v[122:125], v[174:177], v[58:61]
	v_mfma_f32_16x16x32_bf16 v[42:45], v[122:125], v[182:185], v[42:45]
	v_mfma_f32_16x16x32_bf16 v[42:45], v[126:129], v[186:189], v[42:45]
	v_mfma_f32_16x16x32_bf16 v[46:49], v[118:121], v[186:189], v[46:49]
	v_mfma_f32_16x16x32_bf16 v[46:49], v[114:117], v[182:185], v[46:49]
	v_mfma_f32_16x16x32_bf16 v[30:33], v[114:117], v[190:193], v[30:33]
	v_mfma_f32_16x16x32_bf16 v[30:33], v[118:121], v[202:205], v[30:33]
	v_mfma_f32_16x16x32_bf16 v[26:29], v[126:129], v[202:205], v[26:29]
	v_mfma_f32_16x16x32_bf16 v[26:29], v[122:125], v[190:193], v[26:29]
	v_mfma_f32_16x16x32_bf16 v[10:13], v[122:125], v[206:209], v[10:13]
	v_mfma_f32_16x16x32_bf16 v[10:13], v[126:129], v[210:213], v[10:13]
	v_mfma_f32_16x16x32_bf16 v[14:17], v[118:121], v[210:213], v[14:17]
	v_mfma_f32_16x16x32_bf16 v[14:17], v[114:117], v[206:209], v[14:17]
	v_mfma_f32_16x16x32_bf16 v[54:57], v[158:161], v[174:177], v[54:57]
	v_mfma_f32_16x16x32_bf16 v[54:57], v[162:165], v[178:181], v[54:57]
	v_mfma_f32_16x16x32_bf16 v[50:53], v[170:173], v[178:181], v[50:53]
	v_mfma_f32_16x16x32_bf16 v[50:53], v[166:169], v[174:177], v[50:53]
	v_mfma_f32_16x16x32_bf16 v[34:37], v[166:169], v[182:185], v[34:37]
	v_mfma_f32_16x16x32_bf16 v[34:37], v[170:173], v[186:189], v[34:37]
	v_mfma_f32_16x16x32_bf16 v[38:41], v[162:165], v[186:189], v[38:41]
	v_mfma_f32_16x16x32_bf16 v[38:41], v[158:161], v[182:185], v[38:41]
	v_mfma_f32_16x16x32_bf16 v[22:25], v[158:161], v[190:193], v[22:25]
	v_mfma_f32_16x16x32_bf16 v[22:25], v[162:165], v[202:205], v[22:25]
	v_mfma_f32_16x16x32_bf16 v[18:21], v[170:173], v[202:205], v[18:21]
	v_mfma_f32_16x16x32_bf16 v[18:21], v[166:169], v[190:193], v[18:21]
	v_mfma_f32_16x16x32_bf16 v[2:5], v[166:169], v[206:209], v[2:5]
	v_mfma_f32_16x16x32_bf16 v[2:5], v[170:173], v[210:213], v[2:5]
	v_mfma_f32_16x16x32_bf16 v[6:9], v[162:165], v[210:213], v[6:9]
	v_mfma_f32_16x16x32_bf16 v[6:9], v[158:161], v[206:209], v[6:9]
	s_barrier
	s_setprio 0
	s_add_i32 s66, 0, 0x18000
	s_add_i32 s67, 0, 0x1c000
	v_add_u32_e32 v126, s66, v156
	v_add_u32_e32 v170, s67, v156
	ds_read_b128 v[114:117], v126
	ds_read_b128 v[118:121], v126 offset:1024
	ds_read_b128 v[122:125], v126 offset:2048
	ds_read_b128 v[126:129], v126 offset:3072
	ds_read_b128 v[158:161], v170
	ds_read_b128 v[162:165], v170 offset:1024
	ds_read_b128 v[166:169], v170 offset:2048
	ds_read_b128 v[170:173], v170 offset:3072
	s_add_u32 s36, s36, 0x80000
	s_addc_u32 s37, s37, 0
	s_mov_b32 m0, s51
	v_lshl_add_u64 v[230:231], s[36:37], 0, v[146:147]
	ds_read_b128 v[174:177], v157 offset:32768
	ds_read_b128 v[178:181], v157 offset:33792
	ds_read_b128 v[182:185], v157 offset:34816
	ds_read_b128 v[186:189], v157 offset:35840
	ds_read_b128 v[190:193], v157 offset:36864
	ds_read_b128 v[202:205], v157 offset:37888
	ds_read_b128 v[206:209], v157 offset:38912
	ds_read_b128 v[210:213], v157 offset:39936
	global_load_lds_dwordx4 v[230:231], off
	v_lshl_add_u64 v[230:231], s[36:37], 0, v[148:149]
	s_mov_b32 m0, s52
	s_nop 0
	global_load_lds_dwordx4 v[230:231], off
	s_waitcnt vmcnt(8)
	s_waitcnt lgkmcnt(0)
	s_setprio 1
	s_barrier
	v_mfma_f32_16x16x32_bf16 v[142:145], v[114:117], v[174:177], v[142:145]
	v_mfma_f32_16x16x32_bf16 v[142:145], v[118:121], v[178:181], v[142:145]
	v_mfma_f32_16x16x32_bf16 v[138:141], v[126:129], v[178:181], v[138:141]
	v_mfma_f32_16x16x32_bf16 v[138:141], v[122:125], v[174:177], v[138:141]
	v_mfma_f32_16x16x32_bf16 v[106:109], v[122:125], v[182:185], v[106:109]
	v_mfma_f32_16x16x32_bf16 v[106:109], v[126:129], v[186:189], v[106:109]
	v_mfma_f32_16x16x32_bf16 v[110:113], v[118:121], v[186:189], v[110:113]
	v_mfma_f32_16x16x32_bf16 v[110:113], v[114:117], v[182:185], v[110:113]
	v_mfma_f32_16x16x32_bf16 v[94:97], v[114:117], v[190:193], v[94:97]
	v_mfma_f32_16x16x32_bf16 v[94:97], v[118:121], v[202:205], v[94:97]
	v_mfma_f32_16x16x32_bf16 v[90:93], v[126:129], v[202:205], v[90:93]
	v_mfma_f32_16x16x32_bf16 v[90:93], v[122:125], v[190:193], v[90:93]
	v_mfma_f32_16x16x32_bf16 v[74:77], v[122:125], v[206:209], v[74:77]
	v_mfma_f32_16x16x32_bf16 v[74:77], v[126:129], v[210:213], v[74:77]
	v_mfma_f32_16x16x32_bf16 v[78:81], v[118:121], v[210:213], v[78:81]
	v_mfma_f32_16x16x32_bf16 v[78:81], v[114:117], v[206:209], v[78:81]
	v_mfma_f32_16x16x32_bf16 v[134:137], v[158:161], v[174:177], v[134:137]
	v_mfma_f32_16x16x32_bf16 v[134:137], v[162:165], v[178:181], v[134:137]
	v_mfma_f32_16x16x32_bf16 v[130:133], v[170:173], v[178:181], v[130:133]
	v_mfma_f32_16x16x32_bf16 v[130:133], v[166:169], v[174:177], v[130:133]
	v_mfma_f32_16x16x32_bf16 v[98:101], v[166:169], v[182:185], v[98:101]
	v_mfma_f32_16x16x32_bf16 v[98:101], v[170:173], v[186:189], v[98:101]
	v_mfma_f32_16x16x32_bf16 v[102:105], v[162:165], v[186:189], v[102:105]
	v_mfma_f32_16x16x32_bf16 v[102:105], v[158:161], v[182:185], v[102:105]
	v_mfma_f32_16x16x32_bf16 v[86:89], v[158:161], v[190:193], v[86:89]
	v_mfma_f32_16x16x32_bf16 v[86:89], v[162:165], v[202:205], v[86:89]
	v_mfma_f32_16x16x32_bf16 v[82:85], v[170:173], v[202:205], v[82:85]
	v_mfma_f32_16x16x32_bf16 v[82:85], v[166:169], v[190:193], v[82:85]
	v_mfma_f32_16x16x32_bf16 v[66:69], v[166:169], v[206:209], v[66:69]
	v_mfma_f32_16x16x32_bf16 v[66:69], v[170:173], v[210:213], v[66:69]
	v_mfma_f32_16x16x32_bf16 v[70:73], v[162:165], v[210:213], v[70:73]
	v_mfma_f32_16x16x32_bf16 v[70:73], v[158:161], v[206:209], v[70:73]
	s_barrier
	s_setprio 0
	s_add_i32 s36, s66, s48
	v_lshl_add_u64 v[154:155], v[154:155], 0, s[10:11]
	s_mov_b32 m0, s36
	ds_read_b128 v[174:177], v157 offset:49152
	ds_read_b128 v[178:181], v157 offset:50176
	ds_read_b128 v[182:185], v157 offset:51200
	ds_read_b128 v[186:189], v157 offset:52224
	ds_read_b128 v[190:193], v157 offset:53248
	ds_read_b128 v[202:205], v157 offset:54272
	ds_read_b128 v[206:209], v157 offset:55296
	ds_read_b128 v[210:213], v157 offset:56320
	global_load_lds_dwordx4 v[154:155], off
	s_add_i32 m0, s36, 0x2000
	s_add_u32 s30, s30, 0x80080
	v_lshl_add_u64 v[154:155], v[214:215], 0, s[10:11]
	s_addc_u32 s31, s31, 0
	s_add_i32 s36, s67, s48
	global_load_lds_dwordx4 v[154:155], off
	v_lshl_add_u64 v[154:155], s[30:31], 0, v[146:147]
	s_mov_b32 m0, s36
	s_nop 0
	global_load_lds_dwordx4 v[154:155], off
	v_lshl_add_u64 v[154:155], s[30:31], 0, v[148:149]
	s_add_i32 m0, s36, 0x2000
	s_nop 0
	global_load_lds_dwordx4 v[154:155], off
	v_lshl_add_u64 v[154:155], v[216:217], 0, s[10:11]
	s_mov_b32 m0, s53
	s_nop 0
	global_load_lds_dwordx4 v[154:155], off
	v_lshl_add_u64 v[154:155], v[228:229], 0, s[10:11]
	s_mov_b32 m0, s56
	s_nop 0
	global_load_lds_dwordx4 v[154:155], off
	s_waitcnt vmcnt(8)
	s_waitcnt lgkmcnt(0)
	s_setprio 1
	s_barrier
	v_mfma_f32_16x16x32_bf16 v[62:65], v[114:117], v[174:177], v[62:65]
	v_mfma_f32_16x16x32_bf16 v[62:65], v[118:121], v[178:181], v[62:65]
	v_mfma_f32_16x16x32_bf16 v[58:61], v[126:129], v[178:181], v[58:61]
	v_mfma_f32_16x16x32_bf16 v[58:61], v[122:125], v[174:177], v[58:61]
	v_mfma_f32_16x16x32_bf16 v[42:45], v[122:125], v[182:185], v[42:45]
	v_mfma_f32_16x16x32_bf16 v[42:45], v[126:129], v[186:189], v[42:45]
	v_mfma_f32_16x16x32_bf16 v[46:49], v[118:121], v[186:189], v[46:49]
	v_mfma_f32_16x16x32_bf16 v[46:49], v[114:117], v[182:185], v[46:49]
	v_mfma_f32_16x16x32_bf16 v[30:33], v[114:117], v[190:193], v[30:33]
	v_mfma_f32_16x16x32_bf16 v[30:33], v[118:121], v[202:205], v[30:33]
	v_mfma_f32_16x16x32_bf16 v[26:29], v[126:129], v[202:205], v[26:29]
	v_mfma_f32_16x16x32_bf16 v[26:29], v[122:125], v[190:193], v[26:29]
	v_mfma_f32_16x16x32_bf16 v[10:13], v[122:125], v[206:209], v[10:13]
	v_mfma_f32_16x16x32_bf16 v[10:13], v[126:129], v[210:213], v[10:13]
	v_mfma_f32_16x16x32_bf16 v[14:17], v[118:121], v[210:213], v[14:17]
	v_mfma_f32_16x16x32_bf16 v[14:17], v[114:117], v[206:209], v[14:17]
	v_mfma_f32_16x16x32_bf16 v[54:57], v[158:161], v[174:177], v[54:57]
	v_mfma_f32_16x16x32_bf16 v[54:57], v[162:165], v[178:181], v[54:57]
	v_mfma_f32_16x16x32_bf16 v[50:53], v[170:173], v[178:181], v[50:53]
	v_mfma_f32_16x16x32_bf16 v[50:53], v[166:169], v[174:177], v[50:53]
	v_mfma_f32_16x16x32_bf16 v[34:37], v[166:169], v[182:185], v[34:37]
	v_mfma_f32_16x16x32_bf16 v[34:37], v[170:173], v[186:189], v[34:37]
	v_mfma_f32_16x16x32_bf16 v[38:41], v[162:165], v[186:189], v[38:41]
	v_mfma_f32_16x16x32_bf16 v[38:41], v[158:161], v[182:185], v[38:41]
	v_mfma_f32_16x16x32_bf16 v[22:25], v[158:161], v[190:193], v[22:25]
	v_mfma_f32_16x16x32_bf16 v[22:25], v[162:165], v[202:205], v[22:25]
	v_mfma_f32_16x16x32_bf16 v[18:21], v[170:173], v[202:205], v[18:21]
	v_mfma_f32_16x16x32_bf16 v[18:21], v[166:169], v[190:193], v[18:21]
	v_mfma_f32_16x16x32_bf16 v[2:5], v[166:169], v[206:209], v[2:5]
	v_mfma_f32_16x16x32_bf16 v[2:5], v[170:173], v[210:213], v[2:5]
	v_mfma_f32_16x16x32_bf16 v[6:9], v[162:165], v[210:213], v[6:9]
	v_mfma_f32_16x16x32_bf16 v[6:9], v[158:161], v[206:209], v[6:9]
	s_barrier
	s_setprio 0
	s_add_i32 s65, s65, 2
	s_add_u32 s28, s28, 0x100
	s_addc_u32 s29, s29, 0
	s_add_u32 s63, s63, 0x100
	s_addc_u32 s64, s64, 0
	s_cmp_gt_u32 s65, 29
	s_cbranch_scc0 .LBB0_1272
	s_and_b64 vcc, exec, s[18:19]
	s_cbranch_vccz .LBB0_1275
	s_barrier

.LBB0_1346:
	s_or_b32 s20, s30, 1
	s_mul_hi_u32 s31, s20, 0x280000
	s_mul_i32 s42, s20, 0x280000
	s_add_u32 s20, s56, s18
	s_addc_u32 s21, s57, s19
	s_add_u32 s18, s16, 0x280000
	s_addc_u32 s19, s17, 0
	s_add_i32 s44, 0, 0x10000
	s_add_i32 s45, 0, 0x14000
	v_add_u32_e32 v146, s44, v44
	v_add_u32_e32 v162, s45, v44
	ds_read_b128 v[46:49], v146
	ds_read_b128 v[58:61], v146 offset:1024
	ds_read_b128 v[62:65], v146 offset:2048
	ds_read_b128 v[146:149], v146 offset:3072
	ds_read_b128 v[150:153], v162
	ds_read_b128 v[154:157], v162 offset:1024
	ds_read_b128 v[158:161], v162 offset:2048
	ds_read_b128 v[162:165], v162 offset:3072
	s_add_u32 s42, s62, s42
	s_addc_u32 s43, s63, s31
	v_lshl_add_u64 v[206:207], s[42:43], 0, v[194:195]
	s_add_i32 m0, s24, 0xc000
	ds_read_b128 v[166:169], v45
	ds_read_b128 v[170:173], v45 offset:1024
	ds_read_b128 v[174:177], v45 offset:2048
	ds_read_b128 v[178:181], v45 offset:3072
	ds_read_b128 v[182:185], v45 offset:4096
	ds_read_b128 v[186:189], v45 offset:5120
	ds_read_b128 v[190:193], v45 offset:6144
	ds_read_b128 v[202:205], v45 offset:7168
	global_load_lds_dwordx4 v[206:207], off
	v_lshl_add_u64 v[206:207], s[42:43], 0, v[42:43]
	s_add_i32 m0, s24, 0xe000
	s_nop 0
	global_load_lds_dwordx4 v[206:207], off
	s_waitcnt vmcnt(8)
	s_waitcnt lgkmcnt(0)
	s_setprio 1
	s_barrier
	v_mfma_f32_16x16x32_bf16 v[142:145], v[46:49], v[166:169], v[142:145]
	v_mfma_f32_16x16x32_bf16 v[142:145], v[58:61], v[170:173], v[142:145]
	v_mfma_f32_16x16x32_bf16 v[138:141], v[146:149], v[170:173], v[138:141]
	v_mfma_f32_16x16x32_bf16 v[138:141], v[62:65], v[166:169], v[138:141]
	v_mfma_f32_16x16x32_bf16 v[122:125], v[62:65], v[174:177], v[122:125]
	v_mfma_f32_16x16x32_bf16 v[122:125], v[146:149], v[178:181], v[122:125]
	v_mfma_f32_16x16x32_bf16 v[126:129], v[58:61], v[178:181], v[126:129]
	v_mfma_f32_16x16x32_bf16 v[126:129], v[46:49], v[174:177], v[126:129]
	v_mfma_f32_16x16x32_bf16 v[110:113], v[46:49], v[182:185], v[110:113]
	v_mfma_f32_16x16x32_bf16 v[110:113], v[58:61], v[186:189], v[110:113]
	v_mfma_f32_16x16x32_bf16 v[106:109], v[146:149], v[186:189], v[106:109]
	v_mfma_f32_16x16x32_bf16 v[106:109], v[62:65], v[182:185], v[106:109]
	v_mfma_f32_16x16x32_bf16 v[90:93], v[62:65], v[190:193], v[90:93]
	v_mfma_f32_16x16x32_bf16 v[90:93], v[146:149], v[202:205], v[90:93]
	v_mfma_f32_16x16x32_bf16 v[94:97], v[58:61], v[202:205], v[94:97]
	v_mfma_f32_16x16x32_bf16 v[94:97], v[46:49], v[190:193], v[94:97]
	v_mfma_f32_16x16x32_bf16 v[134:137], v[150:153], v[166:169], v[134:137]
	v_mfma_f32_16x16x32_bf16 v[134:137], v[154:157], v[170:173], v[134:137]
	v_mfma_f32_16x16x32_bf16 v[130:133], v[162:165], v[170:173], v[130:133]
	v_mfma_f32_16x16x32_bf16 v[130:133], v[158:161], v[166:169], v[130:133]
	v_mfma_f32_16x16x32_bf16 v[114:117], v[158:161], v[174:177], v[114:117]
	v_mfma_f32_16x16x32_bf16 v[114:117], v[162:165], v[178:181], v[114:117]
	v_mfma_f32_16x16x32_bf16 v[118:121], v[154:157], v[178:181], v[118:121]
	v_mfma_f32_16x16x32_bf16 v[118:121], v[150:153], v[174:177], v[118:121]
	v_mfma_f32_16x16x32_bf16 v[102:105], v[150:153], v[182:185], v[102:105]
	v_mfma_f32_16x16x32_bf16 v[102:105], v[154:157], v[186:189], v[102:105]
	v_mfma_f32_16x16x32_bf16 v[98:101], v[162:165], v[186:189], v[98:101]
	v_mfma_f32_16x16x32_bf16 v[98:101], v[158:161], v[182:185], v[98:101]
	v_mfma_f32_16x16x32_bf16 v[82:85], v[158:161], v[190:193], v[82:85]
	v_mfma_f32_16x16x32_bf16 v[82:85], v[162:165], v[202:205], v[82:85]
	v_mfma_f32_16x16x32_bf16 v[86:89], v[154:157], v[202:205], v[86:89]
	v_mfma_f32_16x16x32_bf16 v[86:89], v[150:153], v[190:193], v[86:89]
	s_barrier
	s_setprio 0
	s_add_i32 s31, s44, s23
	v_lshl_add_u64 v[206:207], s[20:21], 0, v[194:195]
	s_mov_b32 m0, s31
	ds_read_b128 v[166:169], v45 offset:16384
	ds_read_b128 v[170:173], v45 offset:17408
	ds_read_b128 v[174:177], v45 offset:18432
	ds_read_b128 v[178:181], v45 offset:19456
	ds_read_b128 v[182:185], v45 offset:20480
	ds_read_b128 v[186:189], v45 offset:21504
	ds_read_b128 v[190:193], v45 offset:22528
	ds_read_b128 v[202:205], v45 offset:23552
	global_load_lds_dwordx4 v[206:207], off
	s_add_i32 m0, s31, 0x2000
	s_add_u32 s42, s20, 0x4000
	v_lshl_add_u64 v[206:207], s[20:21], 0, v[42:43]
	s_addc_u32 s43, s21, 0
	s_add_i32 s31, s45, s23
	global_load_lds_dwordx4 v[206:207], off
	v_lshl_add_u64 v[206:207], s[42:43], 0, v[194:195]
	s_mov_b32 m0, s31
	s_nop 0
	global_load_lds_dwordx4 v[206:207], off
	v_lshl_add_u64 v[206:207], s[42:43], 0, v[42:43]
	s_add_i32 m0, s31, 0x2000
	s_nop 0
	global_load_lds_dwordx4 v[206:207], off
	v_lshl_add_u64 v[206:207], s[16:17], 0, v[194:195]
	s_mov_b32 m0, s24
	s_nop 0
	global_load_lds_dwordx4 v[206:207], off
	v_lshl_add_u64 v[206:207], s[16:17], 0, v[42:43]
	s_mov_b32 m0, s25
	s_nop 0
	global_load_lds_dwordx4 v[206:207], off
	s_waitcnt vmcnt(8)
	s_waitcnt lgkmcnt(0)
	s_setprio 1
	s_barrier
	v_mfma_f32_16x16x32_bf16 v[78:81], v[46:49], v[166:169], v[78:81]
	v_mfma_f32_16x16x32_bf16 v[78:81], v[58:61], v[170:173], v[78:81]
	v_mfma_f32_16x16x32_bf16 v[74:77], v[146:149], v[170:173], v[74:77]
	v_mfma_f32_16x16x32_bf16 v[74:77], v[62:65], v[166:169], v[74:77]
	v_mfma_f32_16x16x32_bf16 v[50:53], v[62:65], v[174:177], v[50:53]
	v_mfma_f32_16x16x32_bf16 v[50:53], v[146:149], v[178:181], v[50:53]
	v_mfma_f32_16x16x32_bf16 v[54:57], v[58:61], v[178:181], v[54:57]
	v_mfma_f32_16x16x32_bf16 v[54:57], v[46:49], v[174:177], v[54:57]
	v_mfma_f32_16x16x32_bf16 v[30:33], v[46:49], v[182:185], v[30:33]
	v_mfma_f32_16x16x32_bf16 v[30:33], v[58:61], v[186:189], v[30:33]
	v_mfma_f32_16x16x32_bf16 v[26:29], v[146:149], v[186:189], v[26:29]
	v_mfma_f32_16x16x32_bf16 v[26:29], v[62:65], v[182:185], v[26:29]
	v_mfma_f32_16x16x32_bf16 v[10:13], v[62:65], v[190:193], v[10:13]
	v_mfma_f32_16x16x32_bf16 v[10:13], v[146:149], v[202:205], v[10:13]
	v_mfma_f32_16x16x32_bf16 v[14:17], v[58:61], v[202:205], v[14:17]
	v_mfma_f32_16x16x32_bf16 v[14:17], v[46:49], v[190:193], v[14:17]
	v_mfma_f32_16x16x32_bf16 v[38:41], v[150:153], v[174:177], v[38:41]
	v_mfma_f32_16x16x32_bf16 v[34:37], v[158:161], v[174:177], v[34:37]
	v_mfma_f32_16x16x32_bf16 v[22:25], v[150:153], v[182:185], v[22:25]
	v_mfma_f32_16x16x32_bf16 v[18:21], v[158:161], v[182:185], v[18:21]
	v_mfma_f32_16x16x32_bf16 v[6:9], v[150:153], v[190:193], v[6:9]
	v_mfma_f32_16x16x32_bf16 v[2:5], v[158:161], v[190:193], v[2:5]
	v_mfma_f32_16x16x32_bf16 v[46:49], v[150:153], v[166:169], v[70:73]
	v_mfma_f32_16x16x32_bf16 v[58:61], v[158:161], v[166:169], v[66:69]
	v_mfma_f32_16x16x32_bf16 v[38:41], v[154:157], v[178:181], v[38:41]
	v_mfma_f32_16x16x32_bf16 v[34:37], v[162:165], v[178:181], v[34:37]
	v_mfma_f32_16x16x32_bf16 v[22:25], v[154:157], v[186:189], v[22:25]
	v_mfma_f32_16x16x32_bf16 v[18:21], v[162:165], v[186:189], v[18:21]
	v_mfma_f32_16x16x32_bf16 v[6:9], v[154:157], v[202:205], v[6:9]
	v_mfma_f32_16x16x32_bf16 v[2:5], v[162:165], v[202:205], v[2:5]
	v_mfma_f32_16x16x32_bf16 v[46:49], v[154:157], v[170:173], v[46:49]
	v_mfma_f32_16x16x32_bf16 v[58:61], v[162:165], v[170:173], v[58:61]
	s_barrier
	s_setprio 0
	s_add_i32 s31, 0, 0x18000
	s_add_i32 s42, 0, 0x1c000
	v_add_u32_e32 v146, s31, v44
	v_add_u32_e32 v162, s42, v44
	ds_read_b128 v[62:65], v146
	ds_read_b128 v[66:69], v146 offset:1024
	ds_read_b128 v[70:73], v146 offset:2048
	ds_read_b128 v[146:149], v146 offset:3072
	ds_read_b128 v[150:153], v162
	ds_read_b128 v[154:157], v162 offset:1024
	ds_read_b128 v[158:161], v162 offset:2048
	ds_read_b128 v[162:165], v162 offset:3072
	s_add_u32 s16, s16, 0x4000
	s_addc_u32 s17, s17, 0
	s_mov_b32 m0, s26
	v_lshl_add_u64 v[206:207], s[16:17], 0, v[194:195]
	ds_read_b128 v[166:169], v45 offset:32768
	ds_read_b128 v[170:173], v45 offset:33792
	ds_read_b128 v[174:177], v45 offset:34816
	ds_read_b128 v[178:181], v45 offset:35840
	ds_read_b128 v[182:185], v45 offset:36864
	ds_read_b128 v[186:189], v45 offset:37888
	ds_read_b128 v[190:193], v45 offset:38912
	ds_read_b128 v[202:205], v45 offset:39936
	global_load_lds_dwordx4 v[206:207], off
	v_lshl_add_u64 v[206:207], s[16:17], 0, v[42:43]
	s_mov_b32 m0, s27
	s_nop 0
	global_load_lds_dwordx4 v[206:207], off
	s_waitcnt vmcnt(8)
	s_waitcnt lgkmcnt(0)
	s_setprio 1
	s_barrier
	v_mfma_f32_16x16x32_bf16 v[142:145], v[62:65], v[166:169], v[142:145]
	v_mfma_f32_16x16x32_bf16 v[142:145], v[66:69], v[170:173], v[142:145]
	v_mfma_f32_16x16x32_bf16 v[138:141], v[146:149], v[170:173], v[138:141]
	v_mfma_f32_16x16x32_bf16 v[138:141], v[70:73], v[166:169], v[138:141]
	v_mfma_f32_16x16x32_bf16 v[122:125], v[70:73], v[174:177], v[122:125]
	v_mfma_f32_16x16x32_bf16 v[122:125], v[146:149], v[178:181], v[122:125]
	v_mfma_f32_16x16x32_bf16 v[126:129], v[66:69], v[178:181], v[126:129]
	v_mfma_f32_16x16x32_bf16 v[126:129], v[62:65], v[174:177], v[126:129]
	v_mfma_f32_16x16x32_bf16 v[110:113], v[62:65], v[182:185], v[110:113]
	v_mfma_f32_16x16x32_bf16 v[110:113], v[66:69], v[186:189], v[110:113]
	v_mfma_f32_16x16x32_bf16 v[106:109], v[146:149], v[186:189], v[106:109]
	v_mfma_f32_16x16x32_bf16 v[106:109], v[70:73], v[182:185], v[106:109]
	v_mfma_f32_16x16x32_bf16 v[90:93], v[70:73], v[190:193], v[90:93]
	v_mfma_f32_16x16x32_bf16 v[90:93], v[146:149], v[202:205], v[90:93]
	v_mfma_f32_16x16x32_bf16 v[94:97], v[66:69], v[202:205], v[94:97]
	v_mfma_f32_16x16x32_bf16 v[94:97], v[62:65], v[190:193], v[94:97]
	v_mfma_f32_16x16x32_bf16 v[134:137], v[150:153], v[166:169], v[134:137]
	v_mfma_f32_16x16x32_bf16 v[134:137], v[154:157], v[170:173], v[134:137]
	v_mfma_f32_16x16x32_bf16 v[130:133], v[162:165], v[170:173], v[130:133]
	v_mfma_f32_16x16x32_bf16 v[130:133], v[158:161], v[166:169], v[130:133]
	v_mfma_f32_16x16x32_bf16 v[114:117], v[158:161], v[174:177], v[114:117]
	v_mfma_f32_16x16x32_bf16 v[114:117], v[162:165], v[178:181], v[114:117]
	v_mfma_f32_16x16x32_bf16 v[118:121], v[154:157], v[178:181], v[118:121]
	v_mfma_f32_16x16x32_bf16 v[118:121], v[150:153], v[174:177], v[118:121]
	v_mfma_f32_16x16x32_bf16 v[102:105], v[150:153], v[182:185], v[102:105]
	v_mfma_f32_16x16x32_bf16 v[102:105], v[154:157], v[186:189], v[102:105]
	v_mfma_f32_16x16x32_bf16 v[98:101], v[162:165], v[186:189], v[98:101]
	v_mfma_f32_16x16x32_bf16 v[98:101], v[158:161], v[182:185], v[98:101]
	v_mfma_f32_16x16x32_bf16 v[82:85], v[158:161], v[190:193], v[82:85]
	v_mfma_f32_16x16x32_bf16 v[82:85], v[162:165], v[202:205], v[82:85]
	v_mfma_f32_16x16x32_bf16 v[86:89], v[154:157], v[202:205], v[86:89]
	v_mfma_f32_16x16x32_bf16 v[86:89], v[150:153], v[190:193], v[86:89]
	s_barrier
	s_setprio 0
	s_add_u32 s16, s20, 0x40000
	s_addc_u32 s17, s21, 0
	s_add_i32 s31, s31, s23
	v_lshl_add_u64 v[206:207], s[16:17], 0, v[194:195]
	s_mov_b32 m0, s31
	ds_read_b128 v[166:169], v45 offset:49152
	ds_read_b128 v[170:173], v45 offset:50176
	ds_read_b128 v[174:177], v45 offset:51200
	ds_read_b128 v[178:181], v45 offset:52224
	ds_read_b128 v[182:185], v45 offset:53248
	ds_read_b128 v[186:189], v45 offset:54272
	ds_read_b128 v[190:193], v45 offset:55296
	ds_read_b128 v[202:205], v45 offset:56320
	global_load_lds_dwordx4 v[206:207], off
	s_add_i32 m0, s31, 0x2000
	v_lshl_add_u64 v[206:207], s[16:17], 0, v[42:43]
	s_add_u32 s16, s20, 0x44000
	s_addc_u32 s17, s21, 0
	s_add_i32 s20, s42, s23
	global_load_lds_dwordx4 v[206:207], off
	v_lshl_add_u64 v[206:207], s[16:17], 0, v[194:195]
	s_mov_b32 m0, s20
	s_nop 0
	global_load_lds_dwordx4 v[206:207], off
	v_lshl_add_u64 v[206:207], s[16:17], 0, v[42:43]
	s_add_i32 m0, s20, 0x2000
	s_nop 0
	global_load_lds_dwordx4 v[206:207], off
	v_lshl_add_u64 v[206:207], s[18:19], 0, v[194:195]
	s_mov_b32 m0, s28
	s_nop 0
	global_load_lds_dwordx4 v[206:207], off
	v_lshl_add_u64 v[206:207], s[18:19], 0, v[42:43]
	s_mov_b32 m0, s29
	s_nop 0
	global_load_lds_dwordx4 v[206:207], off
	s_waitcnt vmcnt(8)
	s_waitcnt lgkmcnt(0)
	s_setprio 1
	s_barrier
	v_mfma_f32_16x16x32_bf16 v[78:81], v[62:65], v[166:169], v[78:81]
	v_mfma_f32_16x16x32_bf16 v[78:81], v[66:69], v[170:173], v[78:81]
	v_mfma_f32_16x16x32_bf16 v[74:77], v[146:149], v[170:173], v[74:77]
	v_mfma_f32_16x16x32_bf16 v[74:77], v[70:73], v[166:169], v[74:77]
	v_mfma_f32_16x16x32_bf16 v[50:53], v[70:73], v[174:177], v[50:53]
	v_mfma_f32_16x16x32_bf16 v[50:53], v[146:149], v[178:181], v[50:53]
	v_mfma_f32_16x16x32_bf16 v[54:57], v[66:69], v[178:181], v[54:57]
	v_mfma_f32_16x16x32_bf16 v[54:57], v[62:65], v[174:177], v[54:57]
	v_mfma_f32_16x16x32_bf16 v[30:33], v[62:65], v[182:185], v[30:33]
	v_mfma_f32_16x16x32_bf16 v[30:33], v[66:69], v[186:189], v[30:33]
	v_mfma_f32_16x16x32_bf16 v[26:29], v[146:149], v[186:189], v[26:29]
	v_mfma_f32_16x16x32_bf16 v[26:29], v[70:73], v[182:185], v[26:29]
	v_mfma_f32_16x16x32_bf16 v[10:13], v[70:73], v[190:193], v[10:13]
	v_mfma_f32_16x16x32_bf16 v[10:13], v[146:149], v[202:205], v[10:13]
	v_mfma_f32_16x16x32_bf16 v[14:17], v[66:69], v[202:205], v[14:17]
	v_mfma_f32_16x16x32_bf16 v[14:17], v[62:65], v[190:193], v[14:17]
	v_mfma_f32_16x16x32_bf16 v[46:49], v[150:153], v[166:169], v[46:49]
	v_mfma_f32_16x16x32_bf16 v[70:73], v[154:157], v[170:173], v[46:49]
	v_mfma_f32_16x16x32_bf16 v[46:49], v[158:161], v[166:169], v[58:61]
	v_mfma_f32_16x16x32_bf16 v[38:41], v[150:153], v[174:177], v[38:41]
	v_mfma_f32_16x16x32_bf16 v[34:37], v[158:161], v[174:177], v[34:37]
	v_mfma_f32_16x16x32_bf16 v[22:25], v[150:153], v[182:185], v[22:25]
	v_mfma_f32_16x16x32_bf16 v[18:21], v[158:161], v[182:185], v[18:21]
	v_mfma_f32_16x16x32_bf16 v[6:9], v[150:153], v[190:193], v[6:9]
	v_mfma_f32_16x16x32_bf16 v[2:5], v[158:161], v[190:193], v[2:5]
	v_mfma_f32_16x16x32_bf16 v[66:69], v[162:165], v[170:173], v[46:49]
	v_mfma_f32_16x16x32_bf16 v[38:41], v[154:157], v[178:181], v[38:41]
	v_mfma_f32_16x16x32_bf16 v[34:37], v[162:165], v[178:181], v[34:37]
	v_mfma_f32_16x16x32_bf16 v[22:25], v[154:157], v[186:189], v[22:25]
	v_mfma_f32_16x16x32_bf16 v[18:21], v[162:165], v[186:189], v[18:21]
	v_mfma_f32_16x16x32_bf16 v[6:9], v[154:157], v[202:205], v[6:9]
	v_mfma_f32_16x16x32_bf16 v[2:5], v[162:165], v[202:205], v[2:5]
	s_barrier
	s_setprio 0
	s_cmp_gt_u32 s30, 61
	s_mov_b32 s30, s4
	s_cbranch_scc1 .LBB0_1349

.LBB0_1502:
	s_or_b32 s82, s81, 1
	s_add_u32 vcc_lo, s26, vcc_lo
	s_addc_u32 vcc_hi, s27, vcc_hi
	s_and_b64 s[46:47], exec, s[46:47]
	s_cselect_b32 vcc_hi, s19, vcc_hi
	s_cselect_b32 vcc_lo, s21, vcc_lo
	s_add_u32 s46, s44, 0x280000
	s_addc_u32 s47, s45, 0
	s_add_i32 s88, 0, 0x10000
	s_add_i32 s89, 0, 0x14000
	v_add_u32_e32 v62, s88, v184
	v_add_u32_e32 v160, s89, v184
	ds_read_b128 v[50:53], v62
	ds_read_b128 v[54:57], v62 offset:1024
	ds_read_b128 v[58:61], v62 offset:2048
	ds_read_b128 v[62:65], v62 offset:3072
	ds_read_b128 v[146:149], v160
	ds_read_b128 v[150:153], v160 offset:1024
	ds_read_b128 v[156:159], v160 offset:2048
	ds_read_b128 v[160:163], v160 offset:3072
	s_mul_hi_u32 s83, s82, 0x280000
	s_mul_i32 s82, s82, 0x280000
	s_add_u32 s82, s79, s82
	s_addc_u32 s83, s80, s83
	v_lshl_add_u64 v[206:207], s[82:83], 0, v[194:195]
	s_add_i32 m0, s68, 0xc000
	ds_read_b128 v[164:167], v185
	ds_read_b128 v[168:171], v185 offset:1024
	ds_read_b128 v[172:175], v185 offset:2048
	ds_read_b128 v[176:179], v185 offset:3072
	ds_read_b128 v[180:183], v185 offset:4096
	ds_read_b128 v[186:189], v185 offset:5120
	ds_read_b128 v[190:193], v185 offset:6144
	ds_read_b128 v[202:205], v185 offset:7168
	global_load_lds_dwordx4 v[206:207], off
	v_lshl_add_u64 v[206:207], s[82:83], 0, v[154:155]
	s_add_i32 m0, s68, 0xe000
	s_nop 0
	global_load_lds_dwordx4 v[206:207], off
	s_waitcnt vmcnt(8)
	s_waitcnt lgkmcnt(0)
	s_setprio 1
	s_barrier
	v_mfma_f32_16x16x32_bf16 v[142:145], v[50:53], v[164:167], v[142:145]
	v_mfma_f32_16x16x32_bf16 v[142:145], v[54:57], v[168:171], v[142:145]
	v_mfma_f32_16x16x32_bf16 v[138:141], v[62:65], v[168:171], v[138:141]
	v_mfma_f32_16x16x32_bf16 v[138:141], v[58:61], v[164:167], v[138:141]
	v_mfma_f32_16x16x32_bf16 v[122:125], v[58:61], v[172:175], v[122:125]
	v_mfma_f32_16x16x32_bf16 v[122:125], v[62:65], v[176:179], v[122:125]
	v_mfma_f32_16x16x32_bf16 v[126:129], v[54:57], v[176:179], v[126:129]
	v_mfma_f32_16x16x32_bf16 v[126:129], v[50:53], v[172:175], v[126:129]
	v_mfma_f32_16x16x32_bf16 v[110:113], v[50:53], v[180:183], v[110:113]
	v_mfma_f32_16x16x32_bf16 v[110:113], v[54:57], v[186:189], v[110:113]
	v_mfma_f32_16x16x32_bf16 v[106:109], v[62:65], v[186:189], v[106:109]
	v_mfma_f32_16x16x32_bf16 v[106:109], v[58:61], v[180:183], v[106:109]
	v_mfma_f32_16x16x32_bf16 v[90:93], v[58:61], v[190:193], v[90:93]
	v_mfma_f32_16x16x32_bf16 v[90:93], v[62:65], v[202:205], v[90:93]
	v_mfma_f32_16x16x32_bf16 v[94:97], v[54:57], v[202:205], v[94:97]
	v_mfma_f32_16x16x32_bf16 v[94:97], v[50:53], v[190:193], v[94:97]
	v_mfma_f32_16x16x32_bf16 v[134:137], v[146:149], v[164:167], v[134:137]
	v_mfma_f32_16x16x32_bf16 v[134:137], v[150:153], v[168:171], v[134:137]
	v_mfma_f32_16x16x32_bf16 v[130:133], v[160:163], v[168:171], v[130:133]
	v_mfma_f32_16x16x32_bf16 v[130:133], v[156:159], v[164:167], v[130:133]
	v_mfma_f32_16x16x32_bf16 v[114:117], v[156:159], v[172:175], v[114:117]
	v_mfma_f32_16x16x32_bf16 v[114:117], v[160:163], v[176:179], v[114:117]
	v_mfma_f32_16x16x32_bf16 v[118:121], v[150:153], v[176:179], v[118:121]
	v_mfma_f32_16x16x32_bf16 v[118:121], v[146:149], v[172:175], v[118:121]
	v_mfma_f32_16x16x32_bf16 v[102:105], v[146:149], v[180:183], v[102:105]
	v_mfma_f32_16x16x32_bf16 v[102:105], v[150:153], v[186:189], v[102:105]
	v_mfma_f32_16x16x32_bf16 v[98:101], v[160:163], v[186:189], v[98:101]
	v_mfma_f32_16x16x32_bf16 v[98:101], v[156:159], v[180:183], v[98:101]
	v_mfma_f32_16x16x32_bf16 v[82:85], v[156:159], v[190:193], v[82:85]
	v_mfma_f32_16x16x32_bf16 v[82:85], v[160:163], v[202:205], v[82:85]
	v_mfma_f32_16x16x32_bf16 v[86:89], v[150:153], v[202:205], v[86:89]
	v_mfma_f32_16x16x32_bf16 v[86:89], v[146:149], v[190:193], v[86:89]
	s_barrier
	s_setprio 0
	s_add_i32 s82, s88, s67
	v_lshl_add_u64 v[206:207], vcc, 0, v[194:195]
	s_mov_b32 m0, s82
	ds_read_b128 v[164:167], v185 offset:16384
	ds_read_b128 v[168:171], v185 offset:17408
	ds_read_b128 v[172:175], v185 offset:18432
	ds_read_b128 v[176:179], v185 offset:19456
	ds_read_b128 v[180:183], v185 offset:20480
	ds_read_b128 v[186:189], v185 offset:21504
	ds_read_b128 v[190:193], v185 offset:22528
	ds_read_b128 v[202:205], v185 offset:23552
	global_load_lds_dwordx4 v[206:207], off
	s_add_i32 m0, s82, 0x2000
	s_add_u32 s82, vcc_lo, 0x4000
	v_lshl_add_u64 v[206:207], vcc, 0, v[154:155]
	s_addc_u32 s83, vcc_hi, 0
	s_add_i32 s88, s89, s67
	global_load_lds_dwordx4 v[206:207], off
	v_lshl_add_u64 v[206:207], s[82:83], 0, v[194:195]
	s_mov_b32 m0, s88
	s_nop 0
	global_load_lds_dwordx4 v[206:207], off
	v_lshl_add_u64 v[206:207], s[82:83], 0, v[154:155]
	s_add_i32 m0, s88, 0x2000
	s_nop 0
	global_load_lds_dwordx4 v[206:207], off
	v_lshl_add_u64 v[206:207], s[44:45], 0, v[194:195]
	s_mov_b32 m0, s68
	s_nop 0
	global_load_lds_dwordx4 v[206:207], off
	v_lshl_add_u64 v[206:207], s[44:45], 0, v[154:155]
	s_mov_b32 m0, s69
	s_nop 0
	global_load_lds_dwordx4 v[206:207], off
	s_waitcnt vmcnt(8)
	s_waitcnt lgkmcnt(0)
	s_setprio 1
	s_barrier
	v_mfma_f32_16x16x32_bf16 v[78:81], v[50:53], v[164:167], v[78:81]
	v_mfma_f32_16x16x32_bf16 v[78:81], v[54:57], v[168:171], v[78:81]
	v_mfma_f32_16x16x32_bf16 v[74:77], v[62:65], v[168:171], v[74:77]
	v_mfma_f32_16x16x32_bf16 v[74:77], v[58:61], v[164:167], v[74:77]
	v_mfma_f32_16x16x32_bf16 v[42:45], v[58:61], v[172:175], v[42:45]
	v_mfma_f32_16x16x32_bf16 v[42:45], v[62:65], v[176:179], v[42:45]
	v_mfma_f32_16x16x32_bf16 v[46:49], v[54:57], v[176:179], v[46:49]
	v_mfma_f32_16x16x32_bf16 v[46:49], v[50:53], v[172:175], v[46:49]
	v_mfma_f32_16x16x32_bf16 v[30:33], v[50:53], v[180:183], v[30:33]
	v_mfma_f32_16x16x32_bf16 v[30:33], v[54:57], v[186:189], v[30:33]
	v_mfma_f32_16x16x32_bf16 v[26:29], v[62:65], v[186:189], v[26:29]
	v_mfma_f32_16x16x32_bf16 v[26:29], v[58:61], v[180:183], v[26:29]
	v_mfma_f32_16x16x32_bf16 v[10:13], v[58:61], v[190:193], v[10:13]
	v_mfma_f32_16x16x32_bf16 v[10:13], v[62:65], v[202:205], v[10:13]
	v_mfma_f32_16x16x32_bf16 v[14:17], v[54:57], v[202:205], v[14:17]
	v_mfma_f32_16x16x32_bf16 v[14:17], v[50:53], v[190:193], v[14:17]
	v_mfma_f32_16x16x32_bf16 v[38:41], v[146:149], v[172:175], v[38:41]
	v_mfma_f32_16x16x32_bf16 v[34:37], v[156:159], v[172:175], v[34:37]
	v_mfma_f32_16x16x32_bf16 v[22:25], v[146:149], v[180:183], v[22:25]
	v_mfma_f32_16x16x32_bf16 v[18:21], v[156:159], v[180:183], v[18:21]
	v_mfma_f32_16x16x32_bf16 v[6:9], v[146:149], v[190:193], v[6:9]
	v_mfma_f32_16x16x32_bf16 v[2:5], v[156:159], v[190:193], v[2:5]
	v_mfma_f32_16x16x32_bf16 v[50:53], v[146:149], v[164:167], v[70:73]
	v_mfma_f32_16x16x32_bf16 v[54:57], v[156:159], v[164:167], v[66:69]
	v_mfma_f32_16x16x32_bf16 v[38:41], v[150:153], v[176:179], v[38:41]
	v_mfma_f32_16x16x32_bf16 v[34:37], v[160:163], v[176:179], v[34:37]
	v_mfma_f32_16x16x32_bf16 v[22:25], v[150:153], v[186:189], v[22:25]
	v_mfma_f32_16x16x32_bf16 v[18:21], v[160:163], v[186:189], v[18:21]
	v_mfma_f32_16x16x32_bf16 v[6:9], v[150:153], v[202:205], v[6:9]
	v_mfma_f32_16x16x32_bf16 v[2:5], v[160:163], v[202:205], v[2:5]
	v_mfma_f32_16x16x32_bf16 v[50:53], v[150:153], v[168:171], v[50:53]
	v_mfma_f32_16x16x32_bf16 v[54:57], v[160:163], v[168:171], v[54:57]
	s_barrier
	s_setprio 0
	s_add_i32 s82, 0, 0x18000
	s_add_i32 s83, 0, 0x1c000
	v_add_u32_e32 v70, s82, v184
	v_add_u32_e32 v160, s83, v184
	ds_read_b128 v[58:61], v70
	ds_read_b128 v[62:65], v70 offset:1024
	ds_read_b128 v[66:69], v70 offset:2048
	ds_read_b128 v[70:73], v70 offset:3072
	ds_read_b128 v[146:149], v160
	ds_read_b128 v[150:153], v160 offset:1024
	ds_read_b128 v[156:159], v160 offset:2048
	ds_read_b128 v[160:163], v160 offset:3072
	s_add_u32 s44, s44, 0x4000
	s_addc_u32 s45, s45, 0
	s_mov_b32 m0, s72
	v_lshl_add_u64 v[206:207], s[44:45], 0, v[194:195]
	ds_read_b128 v[164:167], v185 offset:32768
	ds_read_b128 v[168:171], v185 offset:33792
	ds_read_b128 v[172:175], v185 offset:34816
	ds_read_b128 v[176:179], v185 offset:35840
	ds_read_b128 v[180:183], v185 offset:36864
	ds_read_b128 v[186:189], v185 offset:37888
	ds_read_b128 v[190:193], v185 offset:38912
	ds_read_b128 v[202:205], v185 offset:39936
	global_load_lds_dwordx4 v[206:207], off
	v_lshl_add_u64 v[206:207], s[44:45], 0, v[154:155]
	s_mov_b32 m0, s73
	s_nop 0
	global_load_lds_dwordx4 v[206:207], off
	s_waitcnt vmcnt(8)
	s_waitcnt lgkmcnt(0)
	s_setprio 1
	s_barrier
	v_mfma_f32_16x16x32_bf16 v[142:145], v[58:61], v[164:167], v[142:145]
	v_mfma_f32_16x16x32_bf16 v[142:145], v[62:65], v[168:171], v[142:145]
	v_mfma_f32_16x16x32_bf16 v[138:141], v[70:73], v[168:171], v[138:141]
	v_mfma_f32_16x16x32_bf16 v[138:141], v[66:69], v[164:167], v[138:141]
	v_mfma_f32_16x16x32_bf16 v[122:125], v[66:69], v[172:175], v[122:125]
	v_mfma_f32_16x16x32_bf16 v[122:125], v[70:73], v[176:179], v[122:125]
	v_mfma_f32_16x16x32_bf16 v[126:129], v[62:65], v[176:179], v[126:129]
	v_mfma_f32_16x16x32_bf16 v[126:129], v[58:61], v[172:175], v[126:129]
	v_mfma_f32_16x16x32_bf16 v[110:113], v[58:61], v[180:183], v[110:113]
	v_mfma_f32_16x16x32_bf16 v[110:113], v[62:65], v[186:189], v[110:113]
	v_mfma_f32_16x16x32_bf16 v[106:109], v[70:73], v[186:189], v[106:109]
	v_mfma_f32_16x16x32_bf16 v[106:109], v[66:69], v[180:183], v[106:109]
	v_mfma_f32_16x16x32_bf16 v[90:93], v[66:69], v[190:193], v[90:93]
	v_mfma_f32_16x16x32_bf16 v[90:93], v[70:73], v[202:205], v[90:93]
	v_mfma_f32_16x16x32_bf16 v[94:97], v[62:65], v[202:205], v[94:97]
	v_mfma_f32_16x16x32_bf16 v[94:97], v[58:61], v[190:193], v[94:97]
	v_mfma_f32_16x16x32_bf16 v[134:137], v[146:149], v[164:167], v[134:137]
	v_mfma_f32_16x16x32_bf16 v[134:137], v[150:153], v[168:171], v[134:137]
	v_mfma_f32_16x16x32_bf16 v[130:133], v[160:163], v[168:171], v[130:133]
	v_mfma_f32_16x16x32_bf16 v[130:133], v[156:159], v[164:167], v[130:133]
	v_mfma_f32_16x16x32_bf16 v[114:117], v[156:159], v[172:175], v[114:117]
	v_mfma_f32_16x16x32_bf16 v[114:117], v[160:163], v[176:179], v[114:117]
	v_mfma_f32_16x16x32_bf16 v[118:121], v[150:153], v[176:179], v[118:121]
	v_mfma_f32_16x16x32_bf16 v[118:121], v[146:149], v[172:175], v[118:121]
	v_mfma_f32_16x16x32_bf16 v[102:105], v[146:149], v[180:183], v[102:105]
	v_mfma_f32_16x16x32_bf16 v[102:105], v[150:153], v[186:189], v[102:105]
	v_mfma_f32_16x16x32_bf16 v[98:101], v[160:163], v[186:189], v[98:101]
	v_mfma_f32_16x16x32_bf16 v[98:101], v[156:159], v[180:183], v[98:101]
	v_mfma_f32_16x16x32_bf16 v[82:85], v[156:159], v[190:193], v[82:85]
	v_mfma_f32_16x16x32_bf16 v[82:85], v[160:163], v[202:205], v[82:85]
	v_mfma_f32_16x16x32_bf16 v[86:89], v[150:153], v[202:205], v[86:89]
	v_mfma_f32_16x16x32_bf16 v[86:89], v[146:149], v[190:193], v[86:89]
	s_barrier
	s_setprio 0
	s_add_u32 s44, vcc_lo, 0x40000
	s_addc_u32 s45, vcc_hi, 0
	s_add_i32 s82, s82, s67
	v_lshl_add_u64 v[206:207], s[44:45], 0, v[194:195]
	s_mov_b32 m0, s82
	ds_read_b128 v[164:167], v185 offset:49152
	ds_read_b128 v[168:171], v185 offset:50176
	ds_read_b128 v[172:175], v185 offset:51200
	ds_read_b128 v[176:179], v185 offset:52224
	ds_read_b128 v[180:183], v185 offset:53248
	ds_read_b128 v[186:189], v185 offset:54272
	ds_read_b128 v[190:193], v185 offset:55296
	ds_read_b128 v[202:205], v185 offset:56320
	global_load_lds_dwordx4 v[206:207], off
	s_add_i32 m0, s82, 0x2000
	v_lshl_add_u64 v[206:207], s[44:45], 0, v[154:155]
	s_add_u32 s44, vcc_lo, 0x44000
	s_addc_u32 s45, vcc_hi, 0
	s_add_i32 s82, s83, s67
	global_load_lds_dwordx4 v[206:207], off
	v_lshl_add_u64 v[206:207], s[44:45], 0, v[194:195]
	s_mov_b32 m0, s82
	s_nop 0
	global_load_lds_dwordx4 v[206:207], off
	v_lshl_add_u64 v[206:207], s[44:45], 0, v[154:155]
	s_add_i32 m0, s82, 0x2000
	s_nop 0
	global_load_lds_dwordx4 v[206:207], off
	v_lshl_add_u64 v[206:207], s[46:47], 0, v[194:195]
	s_mov_b32 m0, s76
	s_nop 0
	global_load_lds_dwordx4 v[206:207], off
	v_lshl_add_u64 v[206:207], s[46:47], 0, v[154:155]
	s_mov_b32 m0, s77
	s_nop 0
	global_load_lds_dwordx4 v[206:207], off
	s_waitcnt vmcnt(8)
	s_waitcnt lgkmcnt(0)
	s_setprio 1
	s_barrier
	v_mfma_f32_16x16x32_bf16 v[78:81], v[58:61], v[164:167], v[78:81]
	v_mfma_f32_16x16x32_bf16 v[78:81], v[62:65], v[168:171], v[78:81]
	v_mfma_f32_16x16x32_bf16 v[74:77], v[70:73], v[168:171], v[74:77]
	v_mfma_f32_16x16x32_bf16 v[74:77], v[66:69], v[164:167], v[74:77]
	v_mfma_f32_16x16x32_bf16 v[42:45], v[66:69], v[172:175], v[42:45]
	v_mfma_f32_16x16x32_bf16 v[42:45], v[70:73], v[176:179], v[42:45]
	v_mfma_f32_16x16x32_bf16 v[46:49], v[62:65], v[176:179], v[46:49]
	v_mfma_f32_16x16x32_bf16 v[46:49], v[58:61], v[172:175], v[46:49]
	v_mfma_f32_16x16x32_bf16 v[30:33], v[58:61], v[180:183], v[30:33]
	v_mfma_f32_16x16x32_bf16 v[30:33], v[62:65], v[186:189], v[30:33]
	v_mfma_f32_16x16x32_bf16 v[26:29], v[70:73], v[186:189], v[26:29]
	v_mfma_f32_16x16x32_bf16 v[26:29], v[66:69], v[180:183], v[26:29]
	v_mfma_f32_16x16x32_bf16 v[10:13], v[66:69], v[190:193], v[10:13]
	v_mfma_f32_16x16x32_bf16 v[10:13], v[70:73], v[202:205], v[10:13]
	v_mfma_f32_16x16x32_bf16 v[14:17], v[62:65], v[202:205], v[14:17]
	v_mfma_f32_16x16x32_bf16 v[14:17], v[58:61], v[190:193], v[14:17]
	v_mfma_f32_16x16x32_bf16 v[50:53], v[146:149], v[164:167], v[50:53]
	v_mfma_f32_16x16x32_bf16 v[70:73], v[150:153], v[168:171], v[50:53]
	v_mfma_f32_16x16x32_bf16 v[50:53], v[156:159], v[164:167], v[54:57]
	v_mfma_f32_16x16x32_bf16 v[38:41], v[146:149], v[172:175], v[38:41]
	v_mfma_f32_16x16x32_bf16 v[34:37], v[156:159], v[172:175], v[34:37]
	v_mfma_f32_16x16x32_bf16 v[22:25], v[146:149], v[180:183], v[22:25]
	v_mfma_f32_16x16x32_bf16 v[18:21], v[156:159], v[180:183], v[18:21]
	v_mfma_f32_16x16x32_bf16 v[6:9], v[146:149], v[190:193], v[6:9]
	v_mfma_f32_16x16x32_bf16 v[2:5], v[156:159], v[190:193], v[2:5]
	v_mfma_f32_16x16x32_bf16 v[66:69], v[160:163], v[168:171], v[50:53]
	v_mfma_f32_16x16x32_bf16 v[38:41], v[150:153], v[176:179], v[38:41]
	v_mfma_f32_16x16x32_bf16 v[34:37], v[160:163], v[176:179], v[34:37]
	v_mfma_f32_16x16x32_bf16 v[22:25], v[150:153], v[186:189], v[22:25]
	v_mfma_f32_16x16x32_bf16 v[18:21], v[160:163], v[186:189], v[18:21]
	v_mfma_f32_16x16x32_bf16 v[6:9], v[150:153], v[202:205], v[6:9]
	v_mfma_f32_16x16x32_bf16 v[2:5], v[160:163], v[202:205], v[2:5]
	s_barrier
	s_setprio 0
	s_cmpk_gt_u32 s81, 0x7d
	s_mov_b32 s81, s4
	s_cbranch_scc1 .LBB0_1505
